# GEMM phases: last K-iteration drops its closing barrier so the trailing half runs its last MFMA block straight into its epilogue while the leading half starts its epilogue and next-tile load segment e
# speedup vs baseline: 1.0631x; 1.0631x over previous
.LBB0_220:
	ds_read_b128 v[148:151], v173
	ds_read_b128 v[152:155], v173 offset:1024
	ds_read_b128 v[156:159], v173 offset:2048
	ds_read_b128 v[160:163], v173 offset:3072
	ds_read_b128 v[164:167], v174
	ds_read_b128 v[180:183], v174 offset:1024
	ds_read_b128 v[184:187], v174 offset:2048
	ds_read_b128 v[188:191], v174 offset:3072
	s_add_u32 s52, s50, 0xfffc0080
	s_addc_u32 s53, s51, -1
	s_cmp_eq_u32 s66, 12
	s_cselect_b32 s55, s9, s53
	s_cselect_b32 s54, s11, s52
	s_cselect_b32 s53, s20, s45
	s_cselect_b32 s52, s33, s43
	v_lshl_add_u64 v[168:169], s[50:51], 0, v[140:141]
	s_add_i32 m0, s35, 0xc000
	ds_read_b128 v[192:195], v175
	ds_read_b128 v[196:199], v175 offset:1024
	ds_read_b128 v[204:207], v175 offset:2048
	ds_read_b128 v[208:211], v175 offset:3072
	ds_read_b128 v[212:215], v175 offset:4096
	ds_read_b128 v[216:219], v175 offset:5120
	ds_read_b128 v[220:223], v175 offset:6144
	ds_read_b128 v[224:227], v175 offset:7168
	global_load_lds_dwordx4 v[168:169], off
	v_lshl_add_u64 v[168:169], s[50:51], 0, v[142:143]
	s_add_i32 m0, s35, 0xe000
	s_nop 0
	global_load_lds_dwordx4 v[168:169], off
	s_waitcnt vmcnt(8)
	s_waitcnt lgkmcnt(0)
	s_barrier
	s_setprio 1
	s_waitcnt lgkmcnt(0)
	v_mfma_f32_16x16x32_bf16 v[124:127], v[148:151], v[192:195], v[124:127]
	v_mfma_f32_16x16x32_bf16 v[120:123], v[156:159], v[192:195], v[120:123]
	v_mfma_f32_16x16x32_bf16 v[108:111], v[148:151], v[204:207], v[108:111]
	v_mfma_f32_16x16x32_bf16 v[104:107], v[156:159], v[204:207], v[104:107]
	v_mfma_f32_16x16x32_bf16 v[92:95], v[148:151], v[212:215], v[92:95]
	v_mfma_f32_16x16x32_bf16 v[88:91], v[156:159], v[212:215], v[88:91]
	v_mfma_f32_16x16x32_bf16 v[76:79], v[148:151], v[220:223], v[76:79]
	v_mfma_f32_16x16x32_bf16 v[72:75], v[156:159], v[220:223], v[72:75]
	v_mfma_f32_16x16x32_bf16 v[124:127], v[152:155], v[196:199], v[124:127]
	v_mfma_f32_16x16x32_bf16 v[120:123], v[160:163], v[196:199], v[120:123]
	v_mfma_f32_16x16x32_bf16 v[108:111], v[152:155], v[208:211], v[108:111]
	v_mfma_f32_16x16x32_bf16 v[104:107], v[160:163], v[208:211], v[104:107]
	v_mfma_f32_16x16x32_bf16 v[92:95], v[152:155], v[216:219], v[92:95]
	v_mfma_f32_16x16x32_bf16 v[88:91], v[160:163], v[216:219], v[88:91]
	v_mfma_f32_16x16x32_bf16 v[76:79], v[152:155], v[224:227], v[76:79]
	v_mfma_f32_16x16x32_bf16 v[72:75], v[160:163], v[224:227], v[72:75]
	s_setprio 0
	s_setprio 1
	v_mfma_f32_16x16x32_bf16 v[116:119], v[164:167], v[192:195], v[116:119]
	v_mfma_f32_16x16x32_bf16 v[112:115], v[184:187], v[192:195], v[112:115]
	v_mfma_f32_16x16x32_bf16 v[100:103], v[164:167], v[204:207], v[100:103]
	v_mfma_f32_16x16x32_bf16 v[96:99], v[184:187], v[204:207], v[96:99]
	v_mfma_f32_16x16x32_bf16 v[84:87], v[164:167], v[212:215], v[84:87]
	v_mfma_f32_16x16x32_bf16 v[80:83], v[184:187], v[212:215], v[80:83]
	v_mfma_f32_16x16x32_bf16 v[68:71], v[164:167], v[220:223], v[68:71]
	v_mfma_f32_16x16x32_bf16 v[64:67], v[184:187], v[220:223], v[64:67]
	v_mfma_f32_16x16x32_bf16 v[116:119], v[180:183], v[196:199], v[116:119]
	v_mfma_f32_16x16x32_bf16 v[112:115], v[188:191], v[196:199], v[112:115]
	v_mfma_f32_16x16x32_bf16 v[100:103], v[180:183], v[208:211], v[100:103]
	v_mfma_f32_16x16x32_bf16 v[96:99], v[188:191], v[208:211], v[96:99]
	v_mfma_f32_16x16x32_bf16 v[84:87], v[180:183], v[216:219], v[84:87]
	v_mfma_f32_16x16x32_bf16 v[80:83], v[188:191], v[216:219], v[80:83]
	v_mfma_f32_16x16x32_bf16 v[68:71], v[180:183], v[224:227], v[68:71]
	v_mfma_f32_16x16x32_bf16 v[64:67], v[188:191], v[224:227], v[64:67]
	s_setprio 0
	s_barrier
	s_add_i32 s67, s63, s31
	v_lshl_add_u64 v[168:169], s[52:53], 0, v[130:131]
	s_mov_b32 m0, s67
	ds_read_b128 v[192:195], v175 offset:16384
	ds_read_b128 v[196:199], v175 offset:17408
	ds_read_b128 v[204:207], v175 offset:18432
	ds_read_b128 v[208:211], v175 offset:19456
	ds_read_b128 v[212:215], v175 offset:20480
	ds_read_b128 v[216:219], v175 offset:21504
	ds_read_b128 v[220:223], v175 offset:22528
	ds_read_b128 v[224:227], v175 offset:23552
	global_load_lds_dwordx4 v[168:169], off
	s_add_i32 m0, s67, 0x2000
	s_add_u32 s68, s52, 0x40000
	v_lshl_add_u64 v[200:201], s[52:53], 0, v[134:135]
	s_addc_u32 s69, s53, 0
	s_add_i32 s67, s64, s31
	global_load_lds_dwordx4 v[200:201], off
	v_lshl_add_u64 v[228:229], s[68:69], 0, v[130:131]
	s_mov_b32 m0, s67
	v_lshl_add_u64 v[230:231], s[54:55], 0, v[132:133]
	global_load_lds_dwordx4 v[228:229], off
	v_lshl_add_u64 v[228:229], s[68:69], 0, v[134:135]
	s_add_i32 m0, s67, 0x2000
	s_nop 0
	global_load_lds_dwordx4 v[228:229], off
	v_lshl_add_u64 v[228:229], s[54:55], 0, v[128:129]
	s_mov_b32 m0, s35
	s_nop 0
	global_load_lds_dwordx4 v[228:229], off
	s_mov_b32 m0, s37
	s_nop 0
	global_load_lds_dwordx4 v[230:231], off
	s_waitcnt vmcnt(8)
	s_waitcnt lgkmcnt(0)
	s_barrier
	s_setprio 1
	s_waitcnt lgkmcnt(0)
	v_mfma_f32_16x16x32_bf16 v[60:63], v[148:151], v[192:195], v[60:63]
	v_mfma_f32_16x16x32_bf16 v[56:59], v[156:159], v[192:195], v[56:59]
	v_mfma_f32_16x16x32_bf16 v[44:47], v[148:151], v[204:207], v[44:47]
	v_mfma_f32_16x16x32_bf16 v[40:43], v[156:159], v[204:207], v[40:43]
	v_mfma_f32_16x16x32_bf16 v[28:31], v[148:151], v[212:215], v[28:31]
	v_mfma_f32_16x16x32_bf16 v[24:27], v[156:159], v[212:215], v[24:27]
	v_mfma_f32_16x16x32_bf16 v[12:15], v[148:151], v[220:223], v[12:15]
	v_mfma_f32_16x16x32_bf16 v[8:11], v[156:159], v[220:223], v[8:11]
	v_mfma_f32_16x16x32_bf16 v[60:63], v[152:155], v[196:199], v[60:63]
	v_mfma_f32_16x16x32_bf16 v[56:59], v[160:163], v[196:199], v[56:59]
	v_mfma_f32_16x16x32_bf16 v[44:47], v[152:155], v[208:211], v[44:47]
	v_mfma_f32_16x16x32_bf16 v[40:43], v[160:163], v[208:211], v[40:43]
	v_mfma_f32_16x16x32_bf16 v[28:31], v[152:155], v[216:219], v[28:31]
	v_mfma_f32_16x16x32_bf16 v[24:27], v[160:163], v[216:219], v[24:27]
	v_mfma_f32_16x16x32_bf16 v[12:15], v[152:155], v[224:227], v[12:15]
	v_mfma_f32_16x16x32_bf16 v[8:11], v[160:163], v[224:227], v[8:11]
	s_setprio 0
	s_setprio 1
	v_mfma_f32_16x16x32_bf16 v[52:55], v[164:167], v[192:195], v[52:55]
	v_mfma_f32_16x16x32_bf16 v[48:51], v[184:187], v[192:195], v[48:51]
	v_mfma_f32_16x16x32_bf16 v[36:39], v[164:167], v[204:207], v[36:39]
	v_mfma_f32_16x16x32_bf16 v[32:35], v[184:187], v[204:207], v[32:35]
	v_mfma_f32_16x16x32_bf16 v[20:23], v[164:167], v[212:215], v[20:23]
	v_mfma_f32_16x16x32_bf16 v[16:19], v[184:187], v[212:215], v[16:19]
	v_mfma_f32_16x16x32_bf16 v[4:7], v[164:167], v[220:223], v[4:7]
	v_mfma_f32_16x16x32_bf16 v[0:3], v[184:187], v[220:223], v[0:3]
	v_mfma_f32_16x16x32_bf16 v[52:55], v[180:183], v[196:199], v[52:55]
	v_mfma_f32_16x16x32_bf16 v[48:51], v[188:191], v[196:199], v[48:51]
	v_mfma_f32_16x16x32_bf16 v[36:39], v[180:183], v[208:211], v[36:39]
	v_mfma_f32_16x16x32_bf16 v[32:35], v[188:191], v[208:211], v[32:35]
	v_mfma_f32_16x16x32_bf16 v[20:23], v[180:183], v[216:219], v[20:23]
	v_mfma_f32_16x16x32_bf16 v[16:19], v[188:191], v[216:219], v[16:19]
	v_mfma_f32_16x16x32_bf16 v[4:7], v[180:183], v[224:227], v[4:7]
	v_mfma_f32_16x16x32_bf16 v[0:3], v[188:191], v[224:227], v[0:3]
	s_setprio 0
	s_barrier
	s_add_i32 s67, 0, 0x18000
	v_add_u32_e32 v137, s67, v171
	s_add_i32 s68, 0, 0x1c000
	ds_read_b128 v[148:151], v137
	ds_read_b128 v[152:155], v137 offset:1024
	ds_read_b128 v[156:159], v137 offset:2048
	ds_read_b128 v[160:163], v137 offset:3072
	v_add_u32_e32 v137, s68, v171
	ds_read_b128 v[164:167], v137
	ds_read_b128 v[180:183], v137 offset:1024
	ds_read_b128 v[184:187], v137 offset:2048
	ds_read_b128 v[188:191], v137 offset:3072
	s_add_u32 s54, s54, 0x40000
	s_addc_u32 s55, s55, 0
	s_mov_b32 m0, s39
	v_lshl_add_u64 v[232:233], s[54:55], 0, v[128:129]
	ds_read_b128 v[192:195], v175 offset:32768
	ds_read_b128 v[196:199], v175 offset:33792
	ds_read_b128 v[204:207], v175 offset:34816
	ds_read_b128 v[208:211], v175 offset:35840
	ds_read_b128 v[212:215], v175 offset:36864
	ds_read_b128 v[216:219], v175 offset:37888
	ds_read_b128 v[220:223], v175 offset:38912
	ds_read_b128 v[224:227], v175 offset:39936
	global_load_lds_dwordx4 v[232:233], off
	v_lshl_add_u64 v[232:233], s[54:55], 0, v[132:133]
	s_mov_b32 m0, s41
	s_nop 0
	global_load_lds_dwordx4 v[232:233], off
	s_waitcnt vmcnt(8)
	s_waitcnt lgkmcnt(0)
	s_barrier
	s_setprio 1
	s_waitcnt lgkmcnt(0)
	v_mfma_f32_16x16x32_bf16 v[124:127], v[148:151], v[192:195], v[124:127]
	v_mfma_f32_16x16x32_bf16 v[120:123], v[156:159], v[192:195], v[120:123]
	v_mfma_f32_16x16x32_bf16 v[108:111], v[148:151], v[204:207], v[108:111]
	v_mfma_f32_16x16x32_bf16 v[104:107], v[156:159], v[204:207], v[104:107]
	v_mfma_f32_16x16x32_bf16 v[92:95], v[148:151], v[212:215], v[92:95]
	v_mfma_f32_16x16x32_bf16 v[88:91], v[156:159], v[212:215], v[88:91]
	v_mfma_f32_16x16x32_bf16 v[76:79], v[148:151], v[220:223], v[76:79]
	v_mfma_f32_16x16x32_bf16 v[72:75], v[156:159], v[220:223], v[72:75]
	v_mfma_f32_16x16x32_bf16 v[124:127], v[152:155], v[196:199], v[124:127]
	v_mfma_f32_16x16x32_bf16 v[120:123], v[160:163], v[196:199], v[120:123]
	v_mfma_f32_16x16x32_bf16 v[108:111], v[152:155], v[208:211], v[108:111]
	v_mfma_f32_16x16x32_bf16 v[104:107], v[160:163], v[208:211], v[104:107]
	v_mfma_f32_16x16x32_bf16 v[92:95], v[152:155], v[216:219], v[92:95]
	v_mfma_f32_16x16x32_bf16 v[88:91], v[160:163], v[216:219], v[88:91]
	v_mfma_f32_16x16x32_bf16 v[76:79], v[152:155], v[224:227], v[76:79]
	v_mfma_f32_16x16x32_bf16 v[72:75], v[160:163], v[224:227], v[72:75]
	s_setprio 0
	s_setprio 1
	v_mfma_f32_16x16x32_bf16 v[116:119], v[164:167], v[192:195], v[116:119]
	v_mfma_f32_16x16x32_bf16 v[112:115], v[184:187], v[192:195], v[112:115]
	v_mfma_f32_16x16x32_bf16 v[100:103], v[164:167], v[204:207], v[100:103]
	v_mfma_f32_16x16x32_bf16 v[96:99], v[184:187], v[204:207], v[96:99]
	v_mfma_f32_16x16x32_bf16 v[84:87], v[164:167], v[212:215], v[84:87]
	v_mfma_f32_16x16x32_bf16 v[80:83], v[184:187], v[212:215], v[80:83]
	v_mfma_f32_16x16x32_bf16 v[68:71], v[164:167], v[220:223], v[68:71]
	v_mfma_f32_16x16x32_bf16 v[64:67], v[184:187], v[220:223], v[64:67]
	v_mfma_f32_16x16x32_bf16 v[116:119], v[180:183], v[196:199], v[116:119]
	v_mfma_f32_16x16x32_bf16 v[112:115], v[188:191], v[196:199], v[112:115]
	v_mfma_f32_16x16x32_bf16 v[100:103], v[180:183], v[208:211], v[100:103]
	v_mfma_f32_16x16x32_bf16 v[96:99], v[188:191], v[208:211], v[96:99]
	v_mfma_f32_16x16x32_bf16 v[84:87], v[180:183], v[216:219], v[84:87]
	v_mfma_f32_16x16x32_bf16 v[80:83], v[188:191], v[216:219], v[80:83]
	v_mfma_f32_16x16x32_bf16 v[68:71], v[180:183], v[224:227], v[68:71]
	v_mfma_f32_16x16x32_bf16 v[64:67], v[188:191], v[224:227], v[64:67]
	s_setprio 0
	s_barrier
	s_add_i32 s54, s67, s31
	v_lshl_add_u64 v[168:169], v[168:169], 0, s[22:23]
	s_mov_b32 m0, s54
	ds_read_b128 v[192:195], v175 offset:49152
	ds_read_b128 v[196:199], v175 offset:50176
	ds_read_b128 v[204:207], v175 offset:51200
	ds_read_b128 v[208:211], v175 offset:52224
	ds_read_b128 v[212:215], v175 offset:53248
	ds_read_b128 v[216:219], v175 offset:54272
	ds_read_b128 v[220:223], v175 offset:55296
	ds_read_b128 v[224:227], v175 offset:56320
	global_load_lds_dwordx4 v[168:169], off
	s_add_i32 m0, s54, 0x2000
	s_add_u32 s52, s52, 0x40080
	v_lshl_add_u64 v[168:169], v[200:201], 0, s[22:23]
	s_addc_u32 s53, s53, 0
	s_add_i32 s54, s68, s31
	global_load_lds_dwordx4 v[168:169], off
	v_lshl_add_u64 v[168:169], s[52:53], 0, v[130:131]
	s_mov_b32 m0, s54
	s_nop 0
	global_load_lds_dwordx4 v[168:169], off
	v_lshl_add_u64 v[168:169], s[52:53], 0, v[134:135]
	s_add_i32 m0, s54, 0x2000
	s_nop 0
	global_load_lds_dwordx4 v[168:169], off
	v_lshl_add_u64 v[168:169], v[228:229], 0, s[22:23]
	s_mov_b32 m0, s60
	s_nop 0
	global_load_lds_dwordx4 v[168:169], off
	v_lshl_add_u64 v[168:169], v[230:231], 0, s[22:23]
	s_mov_b32 m0, s61
	s_nop 0
	global_load_lds_dwordx4 v[168:169], off
	s_waitcnt vmcnt(8)
	s_waitcnt lgkmcnt(0)
	s_barrier
	s_setprio 1
	s_waitcnt lgkmcnt(0)
	v_mfma_f32_16x16x32_bf16 v[60:63], v[148:151], v[192:195], v[60:63]
	v_mfma_f32_16x16x32_bf16 v[56:59], v[156:159], v[192:195], v[56:59]
	v_mfma_f32_16x16x32_bf16 v[44:47], v[148:151], v[204:207], v[44:47]
	v_mfma_f32_16x16x32_bf16 v[40:43], v[156:159], v[204:207], v[40:43]
	v_mfma_f32_16x16x32_bf16 v[28:31], v[148:151], v[212:215], v[28:31]
	v_mfma_f32_16x16x32_bf16 v[24:27], v[156:159], v[212:215], v[24:27]
	v_mfma_f32_16x16x32_bf16 v[12:15], v[148:151], v[220:223], v[12:15]
	v_mfma_f32_16x16x32_bf16 v[8:11], v[156:159], v[220:223], v[8:11]
	v_mfma_f32_16x16x32_bf16 v[60:63], v[152:155], v[196:199], v[60:63]
	v_mfma_f32_16x16x32_bf16 v[56:59], v[160:163], v[196:199], v[56:59]
	v_mfma_f32_16x16x32_bf16 v[44:47], v[152:155], v[208:211], v[44:47]
	v_mfma_f32_16x16x32_bf16 v[40:43], v[160:163], v[208:211], v[40:43]
	v_mfma_f32_16x16x32_bf16 v[28:31], v[152:155], v[216:219], v[28:31]
	v_mfma_f32_16x16x32_bf16 v[24:27], v[160:163], v[216:219], v[24:27]
	v_mfma_f32_16x16x32_bf16 v[12:15], v[152:155], v[224:227], v[12:15]
	v_mfma_f32_16x16x32_bf16 v[8:11], v[160:163], v[224:227], v[8:11]
	s_setprio 0
	s_setprio 1
	v_mfma_f32_16x16x32_bf16 v[52:55], v[164:167], v[192:195], v[52:55]
	v_mfma_f32_16x16x32_bf16 v[48:51], v[184:187], v[192:195], v[48:51]
	v_mfma_f32_16x16x32_bf16 v[36:39], v[164:167], v[204:207], v[36:39]
	v_mfma_f32_16x16x32_bf16 v[32:35], v[184:187], v[204:207], v[32:35]
	v_mfma_f32_16x16x32_bf16 v[20:23], v[164:167], v[212:215], v[20:23]
	v_mfma_f32_16x16x32_bf16 v[16:19], v[184:187], v[212:215], v[16:19]
	v_mfma_f32_16x16x32_bf16 v[4:7], v[164:167], v[220:223], v[4:7]
	v_mfma_f32_16x16x32_bf16 v[0:3], v[184:187], v[220:223], v[0:3]
	v_mfma_f32_16x16x32_bf16 v[52:55], v[180:183], v[196:199], v[52:55]
	v_mfma_f32_16x16x32_bf16 v[48:51], v[188:191], v[196:199], v[48:51]
	v_mfma_f32_16x16x32_bf16 v[36:39], v[180:183], v[208:211], v[36:39]
	v_mfma_f32_16x16x32_bf16 v[32:35], v[188:191], v[208:211], v[32:35]
	v_mfma_f32_16x16x32_bf16 v[20:23], v[180:183], v[216:219], v[20:23]
	v_mfma_f32_16x16x32_bf16 v[16:19], v[188:191], v[216:219], v[16:19]
	v_mfma_f32_16x16x32_bf16 v[4:7], v[180:183], v[224:227], v[4:7]
	v_mfma_f32_16x16x32_bf16 v[0:3], v[188:191], v[224:227], v[0:3]
	s_setprio 0
	s_add_i32 s66, s66, 2
	s_add_u32 s50, s50, 0x100
	s_addc_u32 s51, s51, 0
	s_add_u32 s43, s43, 0x100
	s_addc_u32 s45, s45, 0
	s_cmp_gt_u32 s66, 13
	s_cbranch_scc1 .Lkexit_0
	s_barrier
	s_branch .LBB0_220
.Lkexit_0:
	s_and_b64 vcc, exec, s[24:25]
	s_cbranch_vccz .LBB0_223
	s_barrier

.LBB0_401:
	ds_read_b128 v[128:131], v189
	ds_read_b128 v[132:135], v189 offset:1024
	ds_read_b128 v[136:139], v189 offset:2048
	ds_read_b128 v[140:143], v189 offset:3072
	ds_read_b128 v[144:147], v190
	ds_read_b128 v[148:151], v190 offset:1024
	ds_read_b128 v[168:171], v190 offset:2048
	ds_read_b128 v[172:175], v190 offset:3072
	s_add_u32 s4, s42, 0xfff80080
	s_addc_u32 s5, s43, -1
	s_cmp_eq_u32 s59, 28
	s_cselect_b32 s45, s35, s5
	s_cselect_b32 s44, s41, s4
	s_cselect_b32 s5, s31, s58
	s_cselect_b32 s4, s56, s57
	v_lshl_add_u64 v[184:185], s[42:43], 0, v[160:161]
	s_add_i32 m0, s47, 0xc000
	ds_read_b128 v[176:179], v191
	ds_read_b128 v[180:183], v191 offset:1024
	ds_read_b128 v[194:197], v191 offset:2048
	ds_read_b128 v[198:201], v191 offset:3072
	ds_read_b128 v[204:207], v191 offset:4096
	ds_read_b128 v[208:211], v191 offset:5120
	ds_read_b128 v[212:215], v191 offset:6144
	ds_read_b128 v[216:219], v191 offset:7168
	global_load_lds_dwordx4 v[184:185], off
	v_lshl_add_u64 v[184:185], s[42:43], 0, v[162:163]
	s_add_i32 m0, s47, 0xe000
	s_nop 0
	global_load_lds_dwordx4 v[184:185], off
	s_waitcnt vmcnt(8)
	s_waitcnt lgkmcnt(0)
	s_barrier
	s_setprio 1
	s_waitcnt lgkmcnt(0)
	v_mfma_f32_16x16x32_bf16 v[124:127], v[128:131], v[176:179], v[124:127]
	v_mfma_f32_16x16x32_bf16 v[120:123], v[136:139], v[176:179], v[120:123]
	v_mfma_f32_16x16x32_bf16 v[108:111], v[128:131], v[194:197], v[108:111]
	v_mfma_f32_16x16x32_bf16 v[104:107], v[136:139], v[194:197], v[104:107]
	v_mfma_f32_16x16x32_bf16 v[92:95], v[128:131], v[204:207], v[92:95]
	v_mfma_f32_16x16x32_bf16 v[88:91], v[136:139], v[204:207], v[88:91]
	v_mfma_f32_16x16x32_bf16 v[76:79], v[128:131], v[212:215], v[76:79]
	v_mfma_f32_16x16x32_bf16 v[72:75], v[136:139], v[212:215], v[72:75]
	v_mfma_f32_16x16x32_bf16 v[124:127], v[132:135], v[180:183], v[124:127]
	v_mfma_f32_16x16x32_bf16 v[120:123], v[140:143], v[180:183], v[120:123]
	v_mfma_f32_16x16x32_bf16 v[108:111], v[132:135], v[198:201], v[108:111]
	v_mfma_f32_16x16x32_bf16 v[104:107], v[140:143], v[198:201], v[104:107]
	v_mfma_f32_16x16x32_bf16 v[92:95], v[132:135], v[208:211], v[92:95]
	v_mfma_f32_16x16x32_bf16 v[88:91], v[140:143], v[208:211], v[88:91]
	v_mfma_f32_16x16x32_bf16 v[76:79], v[132:135], v[216:219], v[76:79]
	v_mfma_f32_16x16x32_bf16 v[72:75], v[140:143], v[216:219], v[72:75]
	s_setprio 0
	s_setprio 1
	v_mfma_f32_16x16x32_bf16 v[116:119], v[144:147], v[176:179], v[116:119]
	v_mfma_f32_16x16x32_bf16 v[112:115], v[168:171], v[176:179], v[112:115]
	v_mfma_f32_16x16x32_bf16 v[100:103], v[144:147], v[194:197], v[100:103]
	v_mfma_f32_16x16x32_bf16 v[96:99], v[168:171], v[194:197], v[96:99]
	v_mfma_f32_16x16x32_bf16 v[84:87], v[144:147], v[204:207], v[84:87]
	v_mfma_f32_16x16x32_bf16 v[80:83], v[168:171], v[204:207], v[80:83]
	v_mfma_f32_16x16x32_bf16 v[68:71], v[144:147], v[212:215], v[68:71]
	v_mfma_f32_16x16x32_bf16 v[64:67], v[168:171], v[212:215], v[64:67]
	v_mfma_f32_16x16x32_bf16 v[116:119], v[148:151], v[180:183], v[116:119]
	v_mfma_f32_16x16x32_bf16 v[112:115], v[172:175], v[180:183], v[112:115]
	v_mfma_f32_16x16x32_bf16 v[100:103], v[148:151], v[198:201], v[100:103]
	v_mfma_f32_16x16x32_bf16 v[96:99], v[172:175], v[198:201], v[96:99]
	v_mfma_f32_16x16x32_bf16 v[84:87], v[148:151], v[208:211], v[84:87]
	v_mfma_f32_16x16x32_bf16 v[80:83], v[172:175], v[208:211], v[80:83]
	v_mfma_f32_16x16x32_bf16 v[68:71], v[148:151], v[216:219], v[68:71]
	v_mfma_f32_16x16x32_bf16 v[64:67], v[172:175], v[216:219], v[64:67]
	s_setprio 0
	s_barrier
	s_add_i32 s60, s53, s46
	v_lshl_add_u64 v[184:185], s[4:5], 0, v[154:155]
	s_mov_b32 m0, s60
	ds_read_b128 v[176:179], v191 offset:16384
	ds_read_b128 v[180:183], v191 offset:17408
	ds_read_b128 v[194:197], v191 offset:18432
	ds_read_b128 v[198:201], v191 offset:19456
	ds_read_b128 v[204:207], v191 offset:20480
	ds_read_b128 v[208:211], v191 offset:21504
	ds_read_b128 v[212:215], v191 offset:22528
	ds_read_b128 v[216:219], v191 offset:23552
	global_load_lds_dwordx4 v[184:185], off
	s_add_i32 m0, s60, 0x2000
	s_add_u32 s60, s4, 0x80000
	v_lshl_add_u64 v[220:221], s[4:5], 0, v[158:159]
	s_addc_u32 s61, s5, 0
	s_add_i32 s62, s54, s46
	global_load_lds_dwordx4 v[220:221], off
	v_lshl_add_u64 v[222:223], s[60:61], 0, v[154:155]
	s_mov_b32 m0, s62
	v_lshl_add_u64 v[224:225], s[44:45], 0, v[156:157]
	global_load_lds_dwordx4 v[222:223], off
	v_lshl_add_u64 v[222:223], s[60:61], 0, v[158:159]
	s_add_i32 m0, s62, 0x2000
	s_nop 0
	global_load_lds_dwordx4 v[222:223], off
	v_lshl_add_u64 v[222:223], s[44:45], 0, v[152:153]
	s_mov_b32 m0, s47
	s_nop 0
	global_load_lds_dwordx4 v[222:223], off
	s_mov_b32 m0, s48
	s_nop 0
	global_load_lds_dwordx4 v[224:225], off
	s_waitcnt vmcnt(8)
	s_waitcnt lgkmcnt(0)
	s_barrier
	s_setprio 1
	s_waitcnt lgkmcnt(0)
	v_mfma_f32_16x16x32_bf16 v[60:63], v[128:131], v[176:179], v[60:63]
	v_mfma_f32_16x16x32_bf16 v[56:59], v[136:139], v[176:179], v[56:59]
	v_mfma_f32_16x16x32_bf16 v[44:47], v[128:131], v[194:197], v[44:47]
	v_mfma_f32_16x16x32_bf16 v[40:43], v[136:139], v[194:197], v[40:43]
	v_mfma_f32_16x16x32_bf16 v[28:31], v[128:131], v[204:207], v[28:31]
	v_mfma_f32_16x16x32_bf16 v[24:27], v[136:139], v[204:207], v[24:27]
	v_mfma_f32_16x16x32_bf16 v[12:15], v[128:131], v[212:215], v[12:15]
	v_mfma_f32_16x16x32_bf16 v[8:11], v[136:139], v[212:215], v[8:11]
	v_mfma_f32_16x16x32_bf16 v[60:63], v[132:135], v[180:183], v[60:63]
	v_mfma_f32_16x16x32_bf16 v[56:59], v[140:143], v[180:183], v[56:59]
	v_mfma_f32_16x16x32_bf16 v[44:47], v[132:135], v[198:201], v[44:47]
	v_mfma_f32_16x16x32_bf16 v[40:43], v[140:143], v[198:201], v[40:43]
	v_mfma_f32_16x16x32_bf16 v[28:31], v[132:135], v[208:211], v[28:31]
	v_mfma_f32_16x16x32_bf16 v[24:27], v[140:143], v[208:211], v[24:27]
	v_mfma_f32_16x16x32_bf16 v[12:15], v[132:135], v[216:219], v[12:15]
	v_mfma_f32_16x16x32_bf16 v[8:11], v[140:143], v[216:219], v[8:11]
	s_setprio 0
	s_setprio 1
	v_mfma_f32_16x16x32_bf16 v[52:55], v[144:147], v[176:179], v[52:55]
	v_mfma_f32_16x16x32_bf16 v[48:51], v[168:171], v[176:179], v[48:51]
	v_mfma_f32_16x16x32_bf16 v[36:39], v[144:147], v[194:197], v[36:39]
	v_mfma_f32_16x16x32_bf16 v[32:35], v[168:171], v[194:197], v[32:35]
	v_mfma_f32_16x16x32_bf16 v[20:23], v[144:147], v[204:207], v[20:23]
	v_mfma_f32_16x16x32_bf16 v[16:19], v[168:171], v[204:207], v[16:19]
	v_mfma_f32_16x16x32_bf16 v[4:7], v[144:147], v[212:215], v[4:7]
	v_mfma_f32_16x16x32_bf16 v[0:3], v[168:171], v[212:215], v[0:3]
	v_mfma_f32_16x16x32_bf16 v[52:55], v[148:151], v[180:183], v[52:55]
	v_mfma_f32_16x16x32_bf16 v[48:51], v[172:175], v[180:183], v[48:51]
	v_mfma_f32_16x16x32_bf16 v[36:39], v[148:151], v[198:201], v[36:39]
	v_mfma_f32_16x16x32_bf16 v[32:35], v[172:175], v[198:201], v[32:35]
	v_mfma_f32_16x16x32_bf16 v[20:23], v[148:151], v[208:211], v[20:23]
	v_mfma_f32_16x16x32_bf16 v[16:19], v[172:175], v[208:211], v[16:19]
	v_mfma_f32_16x16x32_bf16 v[4:7], v[148:151], v[216:219], v[4:7]
	v_mfma_f32_16x16x32_bf16 v[0:3], v[172:175], v[216:219], v[0:3]
	s_setprio 0
	s_barrier
	s_add_i32 s60, 0, 0x18000
	s_add_i32 s61, 0, 0x1c000
	v_add_u32_e32 v140, s60, v187
	v_add_u32_e32 v172, s61, v187
	ds_read_b128 v[128:131], v140
	ds_read_b128 v[132:135], v140 offset:1024
	ds_read_b128 v[136:139], v140 offset:2048
	ds_read_b128 v[140:143], v140 offset:3072
	ds_read_b128 v[144:147], v172
	ds_read_b128 v[148:151], v172 offset:1024
	ds_read_b128 v[168:171], v172 offset:2048
	ds_read_b128 v[172:175], v172 offset:3072
	s_add_u32 s44, s44, 0x80000
	s_addc_u32 s45, s45, 0
	s_mov_b32 m0, s49
	v_lshl_add_u64 v[226:227], s[44:45], 0, v[152:153]
	ds_read_b128 v[176:179], v191 offset:32768
	ds_read_b128 v[180:183], v191 offset:33792
	ds_read_b128 v[194:197], v191 offset:34816
	ds_read_b128 v[198:201], v191 offset:35840
	ds_read_b128 v[204:207], v191 offset:36864
	ds_read_b128 v[208:211], v191 offset:37888
	ds_read_b128 v[212:215], v191 offset:38912
	ds_read_b128 v[216:219], v191 offset:39936
	global_load_lds_dwordx4 v[226:227], off
	v_lshl_add_u64 v[226:227], s[44:45], 0, v[156:157]
	s_mov_b32 m0, s50
	s_nop 0
	global_load_lds_dwordx4 v[226:227], off
	s_waitcnt vmcnt(8)
	s_waitcnt lgkmcnt(0)
	s_barrier
	s_setprio 1
	s_waitcnt lgkmcnt(0)
	v_mfma_f32_16x16x32_bf16 v[124:127], v[128:131], v[176:179], v[124:127]
	v_mfma_f32_16x16x32_bf16 v[120:123], v[136:139], v[176:179], v[120:123]
	v_mfma_f32_16x16x32_bf16 v[108:111], v[128:131], v[194:197], v[108:111]
	v_mfma_f32_16x16x32_bf16 v[104:107], v[136:139], v[194:197], v[104:107]
	v_mfma_f32_16x16x32_bf16 v[92:95], v[128:131], v[204:207], v[92:95]
	v_mfma_f32_16x16x32_bf16 v[88:91], v[136:139], v[204:207], v[88:91]
	v_mfma_f32_16x16x32_bf16 v[76:79], v[128:131], v[212:215], v[76:79]
	v_mfma_f32_16x16x32_bf16 v[72:75], v[136:139], v[212:215], v[72:75]
	v_mfma_f32_16x16x32_bf16 v[124:127], v[132:135], v[180:183], v[124:127]
	v_mfma_f32_16x16x32_bf16 v[120:123], v[140:143], v[180:183], v[120:123]
	v_mfma_f32_16x16x32_bf16 v[108:111], v[132:135], v[198:201], v[108:111]
	v_mfma_f32_16x16x32_bf16 v[104:107], v[140:143], v[198:201], v[104:107]
	v_mfma_f32_16x16x32_bf16 v[92:95], v[132:135], v[208:211], v[92:95]
	v_mfma_f32_16x16x32_bf16 v[88:91], v[140:143], v[208:211], v[88:91]
	v_mfma_f32_16x16x32_bf16 v[76:79], v[132:135], v[216:219], v[76:79]
	v_mfma_f32_16x16x32_bf16 v[72:75], v[140:143], v[216:219], v[72:75]
	s_setprio 0
	s_setprio 1
	v_mfma_f32_16x16x32_bf16 v[116:119], v[144:147], v[176:179], v[116:119]
	v_mfma_f32_16x16x32_bf16 v[112:115], v[168:171], v[176:179], v[112:115]
	v_mfma_f32_16x16x32_bf16 v[100:103], v[144:147], v[194:197], v[100:103]
	v_mfma_f32_16x16x32_bf16 v[96:99], v[168:171], v[194:197], v[96:99]
	v_mfma_f32_16x16x32_bf16 v[84:87], v[144:147], v[204:207], v[84:87]
	v_mfma_f32_16x16x32_bf16 v[80:83], v[168:171], v[204:207], v[80:83]
	v_mfma_f32_16x16x32_bf16 v[68:71], v[144:147], v[212:215], v[68:71]
	v_mfma_f32_16x16x32_bf16 v[64:67], v[168:171], v[212:215], v[64:67]
	v_mfma_f32_16x16x32_bf16 v[116:119], v[148:151], v[180:183], v[116:119]
	v_mfma_f32_16x16x32_bf16 v[112:115], v[172:175], v[180:183], v[112:115]
	v_mfma_f32_16x16x32_bf16 v[100:103], v[148:151], v[198:201], v[100:103]
	v_mfma_f32_16x16x32_bf16 v[96:99], v[172:175], v[198:201], v[96:99]
	v_mfma_f32_16x16x32_bf16 v[84:87], v[148:151], v[208:211], v[84:87]
	v_mfma_f32_16x16x32_bf16 v[80:83], v[172:175], v[208:211], v[80:83]
	v_mfma_f32_16x16x32_bf16 v[68:71], v[148:151], v[216:219], v[68:71]
	v_mfma_f32_16x16x32_bf16 v[64:67], v[172:175], v[216:219], v[64:67]
	s_setprio 0
	s_barrier
	s_add_i32 s44, s60, s46
	v_lshl_add_u64 v[184:185], v[184:185], 0, s[26:27]
	s_mov_b32 m0, s44
	ds_read_b128 v[176:179], v191 offset:49152
	ds_read_b128 v[180:183], v191 offset:50176
	ds_read_b128 v[194:197], v191 offset:51200
	ds_read_b128 v[198:201], v191 offset:52224
	ds_read_b128 v[204:207], v191 offset:53248
	ds_read_b128 v[208:211], v191 offset:54272
	ds_read_b128 v[212:215], v191 offset:55296
	ds_read_b128 v[216:219], v191 offset:56320
	global_load_lds_dwordx4 v[184:185], off
	s_add_i32 m0, s44, 0x2000
	s_add_u32 s4, s4, 0x80080
	v_lshl_add_u64 v[184:185], v[220:221], 0, s[26:27]
	s_addc_u32 s5, s5, 0
	s_add_i32 s44, s61, s46
	global_load_lds_dwordx4 v[184:185], off
	v_lshl_add_u64 v[184:185], s[4:5], 0, v[154:155]
	s_mov_b32 m0, s44
	s_nop 0
	global_load_lds_dwordx4 v[184:185], off
	v_lshl_add_u64 v[184:185], s[4:5], 0, v[158:159]
	s_add_i32 m0, s44, 0x2000
	s_nop 0
	global_load_lds_dwordx4 v[184:185], off
	v_lshl_add_u64 v[184:185], v[222:223], 0, s[26:27]
	s_mov_b32 m0, s33
	s_nop 0
	global_load_lds_dwordx4 v[184:185], off
	v_lshl_add_u64 v[184:185], v[224:225], 0, s[26:27]
	s_mov_b32 m0, s52
	s_nop 0
	global_load_lds_dwordx4 v[184:185], off
	s_waitcnt vmcnt(8)
	s_waitcnt lgkmcnt(0)
	s_barrier
	s_setprio 1
	s_waitcnt lgkmcnt(0)
	v_mfma_f32_16x16x32_bf16 v[60:63], v[128:131], v[176:179], v[60:63]
	v_mfma_f32_16x16x32_bf16 v[56:59], v[136:139], v[176:179], v[56:59]
	v_mfma_f32_16x16x32_bf16 v[44:47], v[128:131], v[194:197], v[44:47]
	v_mfma_f32_16x16x32_bf16 v[40:43], v[136:139], v[194:197], v[40:43]
	v_mfma_f32_16x16x32_bf16 v[28:31], v[128:131], v[204:207], v[28:31]
	v_mfma_f32_16x16x32_bf16 v[24:27], v[136:139], v[204:207], v[24:27]
	v_mfma_f32_16x16x32_bf16 v[12:15], v[128:131], v[212:215], v[12:15]
	v_mfma_f32_16x16x32_bf16 v[8:11], v[136:139], v[212:215], v[8:11]
	v_mfma_f32_16x16x32_bf16 v[60:63], v[132:135], v[180:183], v[60:63]
	v_mfma_f32_16x16x32_bf16 v[56:59], v[140:143], v[180:183], v[56:59]
	v_mfma_f32_16x16x32_bf16 v[44:47], v[132:135], v[198:201], v[44:47]
	v_mfma_f32_16x16x32_bf16 v[40:43], v[140:143], v[198:201], v[40:43]
	v_mfma_f32_16x16x32_bf16 v[28:31], v[132:135], v[208:211], v[28:31]
	v_mfma_f32_16x16x32_bf16 v[24:27], v[140:143], v[208:211], v[24:27]
	v_mfma_f32_16x16x32_bf16 v[12:15], v[132:135], v[216:219], v[12:15]
	v_mfma_f32_16x16x32_bf16 v[8:11], v[140:143], v[216:219], v[8:11]
	s_setprio 0
	s_setprio 1
	v_mfma_f32_16x16x32_bf16 v[52:55], v[144:147], v[176:179], v[52:55]
	v_mfma_f32_16x16x32_bf16 v[48:51], v[168:171], v[176:179], v[48:51]
	v_mfma_f32_16x16x32_bf16 v[36:39], v[144:147], v[194:197], v[36:39]
	v_mfma_f32_16x16x32_bf16 v[32:35], v[168:171], v[194:197], v[32:35]
	v_mfma_f32_16x16x32_bf16 v[20:23], v[144:147], v[204:207], v[20:23]
	v_mfma_f32_16x16x32_bf16 v[16:19], v[168:171], v[204:207], v[16:19]
	v_mfma_f32_16x16x32_bf16 v[4:7], v[144:147], v[212:215], v[4:7]
	v_mfma_f32_16x16x32_bf16 v[0:3], v[168:171], v[212:215], v[0:3]
	v_mfma_f32_16x16x32_bf16 v[52:55], v[148:151], v[180:183], v[52:55]
	v_mfma_f32_16x16x32_bf16 v[48:51], v[172:175], v[180:183], v[48:51]
	v_mfma_f32_16x16x32_bf16 v[36:39], v[148:151], v[198:201], v[36:39]
	v_mfma_f32_16x16x32_bf16 v[32:35], v[172:175], v[198:201], v[32:35]
	v_mfma_f32_16x16x32_bf16 v[20:23], v[148:151], v[208:211], v[20:23]
	v_mfma_f32_16x16x32_bf16 v[16:19], v[172:175], v[208:211], v[16:19]
	v_mfma_f32_16x16x32_bf16 v[4:7], v[148:151], v[216:219], v[4:7]
	v_mfma_f32_16x16x32_bf16 v[0:3], v[172:175], v[216:219], v[0:3]
	s_setprio 0
	s_add_i32 s59, s59, 2
	s_add_u32 s42, s42, 0x100
	s_addc_u32 s43, s43, 0
	s_add_u32 s57, s57, 0x100
	s_addc_u32 s58, s58, 0
	s_cmp_gt_u32 s59, 29
	s_cbranch_scc1 .Lkexit_1
	s_barrier
	s_branch .LBB0_401
.Lkexit_1:
	s_and_b64 vcc, exec, s[28:29]
	s_cbranch_vccz .LBB0_404
	s_barrier

.LBB0_483:
	ds_read_b128 v[146:149], v169
	ds_read_b128 v[150:153], v169 offset:1024
	ds_read_b128 v[154:157], v169 offset:2048
	ds_read_b128 v[160:163], v169 offset:3072
	ds_read_b128 v[180:183], v171
	ds_read_b128 v[184:187], v171 offset:1024
	ds_read_b128 v[188:191], v171 offset:2048
	ds_read_b128 v[192:195], v171 offset:3072
	s_add_u32 s4, s10, 0xfffc0080
	s_addc_u32 s5, s11, -1
	s_cmp_eq_u32 s56, 12
	s_cselect_b32 s13, s9, s5
	s_cselect_b32 s12, s37, s4
	s_cselect_b32 s5, s35, s55
	s_cselect_b32 s4, s53, s54
	v_lshl_add_u64 v[200:201], s[10:11], 0, v[138:139]
	s_add_i32 m0, s42, 0xc000
	ds_read_b128 v[196:199], v173
	ds_read_b128 v[204:207], v173 offset:1024
	ds_read_b128 v[208:211], v173 offset:2048
	ds_read_b128 v[212:215], v173 offset:3072
	ds_read_b128 v[216:219], v173 offset:4096
	ds_read_b128 v[220:223], v173 offset:5120
	ds_read_b128 v[224:227], v173 offset:6144
	ds_read_b128 v[228:231], v173 offset:7168
	global_load_lds_dwordx4 v[200:201], off
	v_lshl_add_u64 v[200:201], s[10:11], 0, v[140:141]
	s_add_i32 m0, s42, 0xe000
	s_nop 0
	global_load_lds_dwordx4 v[200:201], off
	s_waitcnt vmcnt(8)
	s_waitcnt lgkmcnt(0)
	s_barrier
	s_setprio 1
	s_waitcnt lgkmcnt(0)
	v_mfma_f32_16x16x32_bf16 v[124:127], v[146:149], v[196:199], v[124:127]
	v_mfma_f32_16x16x32_bf16 v[116:119], v[154:157], v[196:199], v[116:119]
	v_mfma_f32_16x16x32_bf16 v[108:111], v[146:149], v[208:211], v[108:111]
	v_mfma_f32_16x16x32_bf16 v[100:103], v[154:157], v[208:211], v[100:103]
	v_mfma_f32_16x16x32_bf16 v[92:95], v[146:149], v[216:219], v[92:95]
	v_mfma_f32_16x16x32_bf16 v[84:87], v[154:157], v[216:219], v[84:87]
	v_mfma_f32_16x16x32_bf16 v[76:79], v[146:149], v[224:227], v[76:79]
	v_mfma_f32_16x16x32_bf16 v[68:71], v[154:157], v[224:227], v[68:71]
	v_mfma_f32_16x16x32_bf16 v[124:127], v[150:153], v[204:207], v[124:127]
	v_mfma_f32_16x16x32_bf16 v[116:119], v[160:163], v[204:207], v[116:119]
	v_mfma_f32_16x16x32_bf16 v[108:111], v[150:153], v[212:215], v[108:111]
	v_mfma_f32_16x16x32_bf16 v[100:103], v[160:163], v[212:215], v[100:103]
	v_mfma_f32_16x16x32_bf16 v[92:95], v[150:153], v[220:223], v[92:95]
	v_mfma_f32_16x16x32_bf16 v[84:87], v[160:163], v[220:223], v[84:87]
	v_mfma_f32_16x16x32_bf16 v[76:79], v[150:153], v[228:231], v[76:79]
	v_mfma_f32_16x16x32_bf16 v[68:71], v[160:163], v[228:231], v[68:71]
	s_setprio 0
	s_setprio 1
	v_mfma_f32_16x16x32_bf16 v[120:123], v[180:183], v[196:199], v[120:123]
	v_mfma_f32_16x16x32_bf16 v[112:115], v[188:191], v[196:199], v[112:115]
	v_mfma_f32_16x16x32_bf16 v[104:107], v[180:183], v[208:211], v[104:107]
	v_mfma_f32_16x16x32_bf16 v[96:99], v[188:191], v[208:211], v[96:99]
	v_mfma_f32_16x16x32_bf16 v[88:91], v[180:183], v[216:219], v[88:91]
	v_mfma_f32_16x16x32_bf16 v[80:83], v[188:191], v[216:219], v[80:83]
	v_mfma_f32_16x16x32_bf16 v[72:75], v[180:183], v[224:227], v[72:75]
	v_mfma_f32_16x16x32_bf16 v[64:67], v[188:191], v[224:227], v[64:67]
	v_mfma_f32_16x16x32_bf16 v[120:123], v[184:187], v[204:207], v[120:123]
	v_mfma_f32_16x16x32_bf16 v[112:115], v[192:195], v[204:207], v[112:115]
	v_mfma_f32_16x16x32_bf16 v[104:107], v[184:187], v[212:215], v[104:107]
	v_mfma_f32_16x16x32_bf16 v[96:99], v[192:195], v[212:215], v[96:99]
	v_mfma_f32_16x16x32_bf16 v[88:91], v[184:187], v[220:223], v[88:91]
	v_mfma_f32_16x16x32_bf16 v[80:83], v[192:195], v[220:223], v[80:83]
	v_mfma_f32_16x16x32_bf16 v[72:75], v[184:187], v[228:231], v[72:75]
	v_mfma_f32_16x16x32_bf16 v[64:67], v[192:195], v[228:231], v[64:67]
	s_setprio 0
	s_barrier
	s_add_i32 s57, s49, s23
	v_lshl_add_u64 v[200:201], s[4:5], 0, v[132:133]
	s_mov_b32 m0, s57
	ds_read_b128 v[196:199], v173 offset:16384
	ds_read_b128 v[204:207], v173 offset:17408
	ds_read_b128 v[208:211], v173 offset:18432
	ds_read_b128 v[212:215], v173 offset:19456
	ds_read_b128 v[216:219], v173 offset:20480
	ds_read_b128 v[220:223], v173 offset:21504
	ds_read_b128 v[224:227], v173 offset:22528
	ds_read_b128 v[228:231], v173 offset:23552
	global_load_lds_dwordx4 v[200:201], off
	s_add_i32 m0, s57, 0x2000
	s_add_u32 s58, s4, 0x40000
	v_lshl_add_u64 v[232:233], s[4:5], 0, v[128:129]
	s_addc_u32 s59, s5, 0
	s_add_i32 s57, s50, s23
	global_load_lds_dwordx4 v[232:233], off
	v_lshl_add_u64 v[234:235], s[58:59], 0, v[132:133]
	s_mov_b32 m0, s57
	v_lshl_add_u64 v[236:237], s[12:13], 0, v[130:131]
	global_load_lds_dwordx4 v[234:235], off
	v_lshl_add_u64 v[234:235], s[58:59], 0, v[128:129]
	s_add_i32 m0, s57, 0x2000
	s_nop 0
	global_load_lds_dwordx4 v[234:235], off
	v_lshl_add_u64 v[234:235], s[12:13], 0, v[134:135]
	s_mov_b32 m0, s42
	s_nop 0
	global_load_lds_dwordx4 v[234:235], off
	s_mov_b32 m0, s43
	s_nop 0
	global_load_lds_dwordx4 v[236:237], off
	s_waitcnt vmcnt(8)
	s_waitcnt lgkmcnt(0)
	s_barrier
	s_setprio 1
	s_waitcnt lgkmcnt(0)
	v_mfma_f32_16x16x32_bf16 v[60:63], v[146:149], v[196:199], v[60:63]
	v_mfma_f32_16x16x32_bf16 v[52:55], v[154:157], v[196:199], v[52:55]
	v_mfma_f32_16x16x32_bf16 v[44:47], v[146:149], v[208:211], v[44:47]
	v_mfma_f32_16x16x32_bf16 v[36:39], v[154:157], v[208:211], v[36:39]
	v_mfma_f32_16x16x32_bf16 v[28:31], v[146:149], v[216:219], v[28:31]
	v_mfma_f32_16x16x32_bf16 v[20:23], v[154:157], v[216:219], v[20:23]
	v_mfma_f32_16x16x32_bf16 v[12:15], v[146:149], v[224:227], v[12:15]
	v_mfma_f32_16x16x32_bf16 v[4:7], v[154:157], v[224:227], v[4:7]
	v_mfma_f32_16x16x32_bf16 v[60:63], v[150:153], v[204:207], v[60:63]
	v_mfma_f32_16x16x32_bf16 v[52:55], v[160:163], v[204:207], v[52:55]
	v_mfma_f32_16x16x32_bf16 v[44:47], v[150:153], v[212:215], v[44:47]
	v_mfma_f32_16x16x32_bf16 v[36:39], v[160:163], v[212:215], v[36:39]
	v_mfma_f32_16x16x32_bf16 v[28:31], v[150:153], v[220:223], v[28:31]
	v_mfma_f32_16x16x32_bf16 v[20:23], v[160:163], v[220:223], v[20:23]
	v_mfma_f32_16x16x32_bf16 v[12:15], v[150:153], v[228:231], v[12:15]
	v_mfma_f32_16x16x32_bf16 v[4:7], v[160:163], v[228:231], v[4:7]
	s_setprio 0
	s_setprio 1
	v_mfma_f32_16x16x32_bf16 v[56:59], v[180:183], v[196:199], v[56:59]
	v_mfma_f32_16x16x32_bf16 v[48:51], v[188:191], v[196:199], v[48:51]
	v_mfma_f32_16x16x32_bf16 v[40:43], v[180:183], v[208:211], v[40:43]
	v_mfma_f32_16x16x32_bf16 v[32:35], v[188:191], v[208:211], v[32:35]
	v_mfma_f32_16x16x32_bf16 v[24:27], v[180:183], v[216:219], v[24:27]
	v_mfma_f32_16x16x32_bf16 v[16:19], v[188:191], v[216:219], v[16:19]
	v_mfma_f32_16x16x32_bf16 v[8:11], v[180:183], v[224:227], v[8:11]
	v_mfma_f32_16x16x32_bf16 v[0:3], v[188:191], v[224:227], v[0:3]
	v_mfma_f32_16x16x32_bf16 v[56:59], v[184:187], v[204:207], v[56:59]
	v_mfma_f32_16x16x32_bf16 v[48:51], v[192:195], v[204:207], v[48:51]
	v_mfma_f32_16x16x32_bf16 v[40:43], v[184:187], v[212:215], v[40:43]
	v_mfma_f32_16x16x32_bf16 v[32:35], v[192:195], v[212:215], v[32:35]
	v_mfma_f32_16x16x32_bf16 v[24:27], v[184:187], v[220:223], v[24:27]
	v_mfma_f32_16x16x32_bf16 v[16:19], v[192:195], v[220:223], v[16:19]
	v_mfma_f32_16x16x32_bf16 v[8:11], v[184:187], v[228:231], v[8:11]
	v_mfma_f32_16x16x32_bf16 v[0:3], v[192:195], v[228:231], v[0:3]
	s_setprio 0
	s_barrier
	s_add_i32 s57, 0, 0x18000
	v_add_u32_e32 v158, s57, v165
	s_add_i32 s58, 0, 0x1c000
	ds_read_b128 v[146:149], v158
	ds_read_b128 v[150:153], v158 offset:1024
	ds_read_b128 v[154:157], v158 offset:2048
	ds_read_b128 v[160:163], v158 offset:3072
	v_add_u32_e32 v158, s58, v165
	ds_read_b128 v[180:183], v158
	ds_read_b128 v[184:187], v158 offset:1024
	ds_read_b128 v[188:191], v158 offset:2048
	ds_read_b128 v[192:195], v158 offset:3072
	s_add_u32 s12, s12, 0x40000
	s_addc_u32 s13, s13, 0
	s_mov_b32 m0, s44
	v_lshl_add_u64 v[238:239], s[12:13], 0, v[134:135]
	ds_read_b128 v[196:199], v173 offset:32768
	ds_read_b128 v[204:207], v173 offset:33792
	ds_read_b128 v[208:211], v173 offset:34816
	ds_read_b128 v[212:215], v173 offset:35840
	ds_read_b128 v[216:219], v173 offset:36864
	ds_read_b128 v[220:223], v173 offset:37888
	ds_read_b128 v[224:227], v173 offset:38912
	ds_read_b128 v[228:231], v173 offset:39936
	global_load_lds_dwordx4 v[238:239], off
	v_lshl_add_u64 v[238:239], s[12:13], 0, v[130:131]
	s_mov_b32 m0, s45
	s_nop 0
	global_load_lds_dwordx4 v[238:239], off
	s_waitcnt vmcnt(8)
	s_waitcnt lgkmcnt(0)
	s_barrier
	s_setprio 1
	s_waitcnt lgkmcnt(0)
	v_mfma_f32_16x16x32_bf16 v[124:127], v[146:149], v[196:199], v[124:127]
	v_mfma_f32_16x16x32_bf16 v[116:119], v[154:157], v[196:199], v[116:119]
	v_mfma_f32_16x16x32_bf16 v[108:111], v[146:149], v[208:211], v[108:111]
	v_mfma_f32_16x16x32_bf16 v[100:103], v[154:157], v[208:211], v[100:103]
	v_mfma_f32_16x16x32_bf16 v[92:95], v[146:149], v[216:219], v[92:95]
	v_mfma_f32_16x16x32_bf16 v[84:87], v[154:157], v[216:219], v[84:87]
	v_mfma_f32_16x16x32_bf16 v[76:79], v[146:149], v[224:227], v[76:79]
	v_mfma_f32_16x16x32_bf16 v[68:71], v[154:157], v[224:227], v[68:71]
	v_mfma_f32_16x16x32_bf16 v[124:127], v[150:153], v[204:207], v[124:127]
	v_mfma_f32_16x16x32_bf16 v[116:119], v[160:163], v[204:207], v[116:119]
	v_mfma_f32_16x16x32_bf16 v[108:111], v[150:153], v[212:215], v[108:111]
	v_mfma_f32_16x16x32_bf16 v[100:103], v[160:163], v[212:215], v[100:103]
	v_mfma_f32_16x16x32_bf16 v[92:95], v[150:153], v[220:223], v[92:95]
	v_mfma_f32_16x16x32_bf16 v[84:87], v[160:163], v[220:223], v[84:87]
	v_mfma_f32_16x16x32_bf16 v[76:79], v[150:153], v[228:231], v[76:79]
	v_mfma_f32_16x16x32_bf16 v[68:71], v[160:163], v[228:231], v[68:71]
	s_setprio 0
	s_setprio 1
	v_mfma_f32_16x16x32_bf16 v[120:123], v[180:183], v[196:199], v[120:123]
	v_mfma_f32_16x16x32_bf16 v[112:115], v[188:191], v[196:199], v[112:115]
	v_mfma_f32_16x16x32_bf16 v[104:107], v[180:183], v[208:211], v[104:107]
	v_mfma_f32_16x16x32_bf16 v[96:99], v[188:191], v[208:211], v[96:99]
	v_mfma_f32_16x16x32_bf16 v[88:91], v[180:183], v[216:219], v[88:91]
	v_mfma_f32_16x16x32_bf16 v[80:83], v[188:191], v[216:219], v[80:83]
	v_mfma_f32_16x16x32_bf16 v[72:75], v[180:183], v[224:227], v[72:75]
	v_mfma_f32_16x16x32_bf16 v[64:67], v[188:191], v[224:227], v[64:67]
	v_mfma_f32_16x16x32_bf16 v[120:123], v[184:187], v[204:207], v[120:123]
	v_mfma_f32_16x16x32_bf16 v[112:115], v[192:195], v[204:207], v[112:115]
	v_mfma_f32_16x16x32_bf16 v[104:107], v[184:187], v[212:215], v[104:107]
	v_mfma_f32_16x16x32_bf16 v[96:99], v[192:195], v[212:215], v[96:99]
	v_mfma_f32_16x16x32_bf16 v[88:91], v[184:187], v[220:223], v[88:91]
	v_mfma_f32_16x16x32_bf16 v[80:83], v[192:195], v[220:223], v[80:83]
	v_mfma_f32_16x16x32_bf16 v[72:75], v[184:187], v[228:231], v[72:75]
	v_mfma_f32_16x16x32_bf16 v[64:67], v[192:195], v[228:231], v[64:67]
	s_setprio 0
	s_barrier
	s_add_i32 s12, s57, s23
	v_lshl_add_u64 v[200:201], v[200:201], 0, s[28:29]
	s_mov_b32 m0, s12
	ds_read_b128 v[196:199], v173 offset:49152
	ds_read_b128 v[204:207], v173 offset:50176
	ds_read_b128 v[208:211], v173 offset:51200
	ds_read_b128 v[212:215], v173 offset:52224
	ds_read_b128 v[216:219], v173 offset:53248
	ds_read_b128 v[220:223], v173 offset:54272
	ds_read_b128 v[224:227], v173 offset:55296
	ds_read_b128 v[228:231], v173 offset:56320
	global_load_lds_dwordx4 v[200:201], off
	s_add_i32 m0, s12, 0x2000
	s_add_u32 s4, s4, 0x40080
	v_lshl_add_u64 v[200:201], v[232:233], 0, s[28:29]
	s_addc_u32 s5, s5, 0
	s_add_i32 s12, s58, s23
	global_load_lds_dwordx4 v[200:201], off
	v_lshl_add_u64 v[200:201], s[4:5], 0, v[132:133]
	s_mov_b32 m0, s12
	s_nop 0
	global_load_lds_dwordx4 v[200:201], off
	v_lshl_add_u64 v[200:201], s[4:5], 0, v[128:129]
	s_add_i32 m0, s12, 0x2000
	s_nop 0
	global_load_lds_dwordx4 v[200:201], off
	v_lshl_add_u64 v[200:201], v[234:235], 0, s[28:29]
	s_mov_b32 m0, s47
	s_nop 0
	global_load_lds_dwordx4 v[200:201], off
	v_lshl_add_u64 v[200:201], v[236:237], 0, s[28:29]
	s_mov_b32 m0, s48
	s_nop 0
	global_load_lds_dwordx4 v[200:201], off
	s_waitcnt vmcnt(8)
	s_waitcnt lgkmcnt(0)
	s_barrier
	s_setprio 1
	s_waitcnt lgkmcnt(0)
	v_mfma_f32_16x16x32_bf16 v[60:63], v[146:149], v[196:199], v[60:63]
	v_mfma_f32_16x16x32_bf16 v[52:55], v[154:157], v[196:199], v[52:55]
	v_mfma_f32_16x16x32_bf16 v[44:47], v[146:149], v[208:211], v[44:47]
	v_mfma_f32_16x16x32_bf16 v[36:39], v[154:157], v[208:211], v[36:39]
	v_mfma_f32_16x16x32_bf16 v[28:31], v[146:149], v[216:219], v[28:31]
	v_mfma_f32_16x16x32_bf16 v[20:23], v[154:157], v[216:219], v[20:23]
	v_mfma_f32_16x16x32_bf16 v[12:15], v[146:149], v[224:227], v[12:15]
	v_mfma_f32_16x16x32_bf16 v[4:7], v[154:157], v[224:227], v[4:7]
	v_mfma_f32_16x16x32_bf16 v[60:63], v[150:153], v[204:207], v[60:63]
	v_mfma_f32_16x16x32_bf16 v[52:55], v[160:163], v[204:207], v[52:55]
	v_mfma_f32_16x16x32_bf16 v[44:47], v[150:153], v[212:215], v[44:47]
	v_mfma_f32_16x16x32_bf16 v[36:39], v[160:163], v[212:215], v[36:39]
	v_mfma_f32_16x16x32_bf16 v[28:31], v[150:153], v[220:223], v[28:31]
	v_mfma_f32_16x16x32_bf16 v[20:23], v[160:163], v[220:223], v[20:23]
	v_mfma_f32_16x16x32_bf16 v[12:15], v[150:153], v[228:231], v[12:15]
	v_mfma_f32_16x16x32_bf16 v[4:7], v[160:163], v[228:231], v[4:7]
	s_setprio 0
	s_setprio 1
	v_mfma_f32_16x16x32_bf16 v[56:59], v[180:183], v[196:199], v[56:59]
	v_mfma_f32_16x16x32_bf16 v[48:51], v[188:191], v[196:199], v[48:51]
	v_mfma_f32_16x16x32_bf16 v[40:43], v[180:183], v[208:211], v[40:43]
	v_mfma_f32_16x16x32_bf16 v[32:35], v[188:191], v[208:211], v[32:35]
	v_mfma_f32_16x16x32_bf16 v[24:27], v[180:183], v[216:219], v[24:27]
	v_mfma_f32_16x16x32_bf16 v[16:19], v[188:191], v[216:219], v[16:19]
	v_mfma_f32_16x16x32_bf16 v[8:11], v[180:183], v[224:227], v[8:11]
	v_mfma_f32_16x16x32_bf16 v[0:3], v[188:191], v[224:227], v[0:3]
	v_mfma_f32_16x16x32_bf16 v[56:59], v[184:187], v[204:207], v[56:59]
	v_mfma_f32_16x16x32_bf16 v[48:51], v[192:195], v[204:207], v[48:51]
	v_mfma_f32_16x16x32_bf16 v[40:43], v[184:187], v[212:215], v[40:43]
	v_mfma_f32_16x16x32_bf16 v[32:35], v[192:195], v[212:215], v[32:35]
	v_mfma_f32_16x16x32_bf16 v[24:27], v[184:187], v[220:223], v[24:27]
	v_mfma_f32_16x16x32_bf16 v[16:19], v[192:195], v[220:223], v[16:19]
	v_mfma_f32_16x16x32_bf16 v[8:11], v[184:187], v[228:231], v[8:11]
	v_mfma_f32_16x16x32_bf16 v[0:3], v[192:195], v[228:231], v[0:3]
	s_setprio 0
	s_add_i32 s56, s56, 2
	s_add_u32 s10, s10, 0x100
	s_addc_u32 s11, s11, 0
	s_add_u32 s54, s54, 0x100
	s_addc_u32 s55, s55, 0
	s_cmp_gt_u32 s56, 13
	s_cbranch_scc1 .Lkexit_2
	s_barrier
	s_branch .LBB0_483
.Lkexit_2:
	s_and_b64 vcc, exec, s[30:31]
	s_cbranch_vccz .LBB0_486
	s_barrier

.LBB0_559:
	ds_read_b128 v[128:131], v189
	ds_read_b128 v[132:135], v189 offset:1024
	ds_read_b128 v[136:139], v189 offset:2048
	ds_read_b128 v[140:143], v189 offset:3072
	ds_read_b128 v[144:147], v190
	ds_read_b128 v[148:151], v190 offset:1024
	ds_read_b128 v[168:171], v190 offset:2048
	ds_read_b128 v[172:175], v190 offset:3072
	s_add_u32 s4, s22, 0x100
	s_addc_u32 s5, s23, 0
	s_cmp_eq_u32 s57, 40
	s_cselect_b32 s41, s11, s5
	s_cselect_b32 s40, s10, s4
	s_cselect_b32 s39, s37, s56
	s_cselect_b32 s38, s36, s55
	v_lshl_add_u64 v[184:185], s[22:23], 0, v[160:161]
	s_add_i32 m0, s43, 0xc000
	ds_read_b128 v[176:179], v191
	ds_read_b128 v[180:183], v191 offset:1024
	ds_read_b128 v[194:197], v191 offset:2048
	ds_read_b128 v[198:201], v191 offset:3072
	ds_read_b128 v[204:207], v191 offset:4096
	ds_read_b128 v[208:211], v191 offset:5120
	ds_read_b128 v[212:215], v191 offset:6144
	ds_read_b128 v[216:219], v191 offset:7168
	global_load_lds_dwordx4 v[184:185], off
	v_lshl_add_u64 v[184:185], s[22:23], 0, v[162:163]
	s_add_i32 m0, s43, 0xe000
	s_nop 0
	global_load_lds_dwordx4 v[184:185], off
	s_waitcnt vmcnt(8)
	s_waitcnt lgkmcnt(0)
	s_barrier
	s_setprio 1
	s_waitcnt lgkmcnt(0)
	v_mfma_f32_16x16x32_bf16 v[124:127], v[128:131], v[176:179], v[124:127]
	v_mfma_f32_16x16x32_bf16 v[120:123], v[136:139], v[176:179], v[120:123]
	v_mfma_f32_16x16x32_bf16 v[108:111], v[128:131], v[194:197], v[108:111]
	v_mfma_f32_16x16x32_bf16 v[104:107], v[136:139], v[194:197], v[104:107]
	v_mfma_f32_16x16x32_bf16 v[92:95], v[128:131], v[204:207], v[92:95]
	v_mfma_f32_16x16x32_bf16 v[88:91], v[136:139], v[204:207], v[88:91]
	v_mfma_f32_16x16x32_bf16 v[76:79], v[128:131], v[212:215], v[76:79]
	v_mfma_f32_16x16x32_bf16 v[72:75], v[136:139], v[212:215], v[72:75]
	v_mfma_f32_16x16x32_bf16 v[124:127], v[132:135], v[180:183], v[124:127]
	v_mfma_f32_16x16x32_bf16 v[120:123], v[140:143], v[180:183], v[120:123]
	v_mfma_f32_16x16x32_bf16 v[108:111], v[132:135], v[198:201], v[108:111]
	v_mfma_f32_16x16x32_bf16 v[104:107], v[140:143], v[198:201], v[104:107]
	v_mfma_f32_16x16x32_bf16 v[92:95], v[132:135], v[208:211], v[92:95]
	v_mfma_f32_16x16x32_bf16 v[88:91], v[140:143], v[208:211], v[88:91]
	v_mfma_f32_16x16x32_bf16 v[76:79], v[132:135], v[216:219], v[76:79]
	v_mfma_f32_16x16x32_bf16 v[72:75], v[140:143], v[216:219], v[72:75]
	s_setprio 0
	s_setprio 1
	v_mfma_f32_16x16x32_bf16 v[116:119], v[144:147], v[176:179], v[116:119]
	v_mfma_f32_16x16x32_bf16 v[112:115], v[168:171], v[176:179], v[112:115]
	v_mfma_f32_16x16x32_bf16 v[100:103], v[144:147], v[194:197], v[100:103]
	v_mfma_f32_16x16x32_bf16 v[96:99], v[168:171], v[194:197], v[96:99]
	v_mfma_f32_16x16x32_bf16 v[84:87], v[144:147], v[204:207], v[84:87]
	v_mfma_f32_16x16x32_bf16 v[80:83], v[168:171], v[204:207], v[80:83]
	v_mfma_f32_16x16x32_bf16 v[68:71], v[144:147], v[212:215], v[68:71]
	v_mfma_f32_16x16x32_bf16 v[64:67], v[168:171], v[212:215], v[64:67]
	v_mfma_f32_16x16x32_bf16 v[116:119], v[148:151], v[180:183], v[116:119]
	v_mfma_f32_16x16x32_bf16 v[112:115], v[172:175], v[180:183], v[112:115]
	v_mfma_f32_16x16x32_bf16 v[100:103], v[148:151], v[198:201], v[100:103]
	v_mfma_f32_16x16x32_bf16 v[96:99], v[172:175], v[198:201], v[96:99]
	v_mfma_f32_16x16x32_bf16 v[84:87], v[148:151], v[208:211], v[84:87]
	v_mfma_f32_16x16x32_bf16 v[80:83], v[172:175], v[208:211], v[80:83]
	v_mfma_f32_16x16x32_bf16 v[68:71], v[148:151], v[216:219], v[68:71]
	v_mfma_f32_16x16x32_bf16 v[64:67], v[172:175], v[216:219], v[64:67]
	s_setprio 0
	s_barrier
	s_add_i32 s22, s49, s42
	v_lshl_add_u64 v[184:185], s[38:39], 0, v[154:155]
	s_mov_b32 m0, s22
	ds_read_b128 v[176:179], v191 offset:16384
	ds_read_b128 v[180:183], v191 offset:17408
	ds_read_b128 v[194:197], v191 offset:18432
	ds_read_b128 v[198:201], v191 offset:19456
	ds_read_b128 v[204:207], v191 offset:20480
	ds_read_b128 v[208:211], v191 offset:21504
	ds_read_b128 v[212:215], v191 offset:22528
	ds_read_b128 v[216:219], v191 offset:23552
	global_load_lds_dwordx4 v[184:185], off
	s_add_i32 m0, s22, 0x2000
	s_add_u32 s22, s38, 0xb0000
	v_lshl_add_u64 v[220:221], s[38:39], 0, v[158:159]
	s_addc_u32 s23, s39, 0
	s_add_i32 s58, s50, s42
	global_load_lds_dwordx4 v[220:221], off
	v_lshl_add_u64 v[222:223], s[22:23], 0, v[154:155]
	s_mov_b32 m0, s58
	v_lshl_add_u64 v[224:225], s[40:41], 0, v[156:157]
	global_load_lds_dwordx4 v[222:223], off
	v_lshl_add_u64 v[222:223], s[22:23], 0, v[158:159]
	s_add_i32 m0, s58, 0x2000
	s_nop 0
	global_load_lds_dwordx4 v[222:223], off
	v_lshl_add_u64 v[222:223], s[40:41], 0, v[152:153]
	s_mov_b32 m0, s43
	s_nop 0
	global_load_lds_dwordx4 v[222:223], off
	s_mov_b32 m0, s44
	s_nop 0
	global_load_lds_dwordx4 v[224:225], off
	s_waitcnt vmcnt(8)
	s_waitcnt lgkmcnt(0)
	s_barrier
	s_setprio 1
	s_waitcnt lgkmcnt(0)
	v_mfma_f32_16x16x32_bf16 v[60:63], v[128:131], v[176:179], v[60:63]
	v_mfma_f32_16x16x32_bf16 v[56:59], v[136:139], v[176:179], v[56:59]
	v_mfma_f32_16x16x32_bf16 v[44:47], v[128:131], v[194:197], v[44:47]
	v_mfma_f32_16x16x32_bf16 v[40:43], v[136:139], v[194:197], v[40:43]
	v_mfma_f32_16x16x32_bf16 v[28:31], v[128:131], v[204:207], v[28:31]
	v_mfma_f32_16x16x32_bf16 v[24:27], v[136:139], v[204:207], v[24:27]
	v_mfma_f32_16x16x32_bf16 v[12:15], v[128:131], v[212:215], v[12:15]
	v_mfma_f32_16x16x32_bf16 v[8:11], v[136:139], v[212:215], v[8:11]
	v_mfma_f32_16x16x32_bf16 v[60:63], v[132:135], v[180:183], v[60:63]
	v_mfma_f32_16x16x32_bf16 v[56:59], v[140:143], v[180:183], v[56:59]
	v_mfma_f32_16x16x32_bf16 v[44:47], v[132:135], v[198:201], v[44:47]
	v_mfma_f32_16x16x32_bf16 v[40:43], v[140:143], v[198:201], v[40:43]
	v_mfma_f32_16x16x32_bf16 v[28:31], v[132:135], v[208:211], v[28:31]
	v_mfma_f32_16x16x32_bf16 v[24:27], v[140:143], v[208:211], v[24:27]
	v_mfma_f32_16x16x32_bf16 v[12:15], v[132:135], v[216:219], v[12:15]
	v_mfma_f32_16x16x32_bf16 v[8:11], v[140:143], v[216:219], v[8:11]
	s_setprio 0
	s_setprio 1
	v_mfma_f32_16x16x32_bf16 v[52:55], v[144:147], v[176:179], v[52:55]
	v_mfma_f32_16x16x32_bf16 v[48:51], v[168:171], v[176:179], v[48:51]
	v_mfma_f32_16x16x32_bf16 v[36:39], v[144:147], v[194:197], v[36:39]
	v_mfma_f32_16x16x32_bf16 v[32:35], v[168:171], v[194:197], v[32:35]
	v_mfma_f32_16x16x32_bf16 v[20:23], v[144:147], v[204:207], v[20:23]
	v_mfma_f32_16x16x32_bf16 v[16:19], v[168:171], v[204:207], v[16:19]
	v_mfma_f32_16x16x32_bf16 v[4:7], v[144:147], v[212:215], v[4:7]
	v_mfma_f32_16x16x32_bf16 v[0:3], v[168:171], v[212:215], v[0:3]
	v_mfma_f32_16x16x32_bf16 v[52:55], v[148:151], v[180:183], v[52:55]
	v_mfma_f32_16x16x32_bf16 v[48:51], v[172:175], v[180:183], v[48:51]
	v_mfma_f32_16x16x32_bf16 v[36:39], v[148:151], v[198:201], v[36:39]
	v_mfma_f32_16x16x32_bf16 v[32:35], v[172:175], v[198:201], v[32:35]
	v_mfma_f32_16x16x32_bf16 v[20:23], v[148:151], v[208:211], v[20:23]
	v_mfma_f32_16x16x32_bf16 v[16:19], v[172:175], v[208:211], v[16:19]
	v_mfma_f32_16x16x32_bf16 v[4:7], v[148:151], v[216:219], v[4:7]
	v_mfma_f32_16x16x32_bf16 v[0:3], v[172:175], v[216:219], v[0:3]
	s_setprio 0
	s_barrier
	s_add_i32 s58, 0, 0x18000
	s_add_i32 s59, 0, 0x1c000
	v_add_u32_e32 v140, s58, v187
	v_add_u32_e32 v172, s59, v187
	ds_read_b128 v[128:131], v140
	ds_read_b128 v[132:135], v140 offset:1024
	ds_read_b128 v[136:139], v140 offset:2048
	ds_read_b128 v[140:143], v140 offset:3072
	ds_read_b128 v[144:147], v172
	ds_read_b128 v[148:151], v172 offset:1024
	ds_read_b128 v[168:171], v172 offset:2048
	ds_read_b128 v[172:175], v172 offset:3072
	s_add_u32 s22, s40, 0xb0000
	s_addc_u32 s23, s41, 0
	s_mov_b32 m0, s45
	v_lshl_add_u64 v[226:227], s[22:23], 0, v[152:153]
	ds_read_b128 v[176:179], v191 offset:32768
	ds_read_b128 v[180:183], v191 offset:33792
	ds_read_b128 v[194:197], v191 offset:34816
	ds_read_b128 v[198:201], v191 offset:35840
	ds_read_b128 v[204:207], v191 offset:36864
	ds_read_b128 v[208:211], v191 offset:37888
	ds_read_b128 v[212:215], v191 offset:38912
	ds_read_b128 v[216:219], v191 offset:39936
	global_load_lds_dwordx4 v[226:227], off
	v_lshl_add_u64 v[226:227], s[22:23], 0, v[156:157]
	s_mov_b32 m0, s46
	s_nop 0
	global_load_lds_dwordx4 v[226:227], off
	s_waitcnt vmcnt(8)
	s_waitcnt lgkmcnt(0)
	s_barrier
	s_setprio 1
	s_waitcnt lgkmcnt(0)
	v_mfma_f32_16x16x32_bf16 v[124:127], v[128:131], v[176:179], v[124:127]
	v_mfma_f32_16x16x32_bf16 v[120:123], v[136:139], v[176:179], v[120:123]
	v_mfma_f32_16x16x32_bf16 v[108:111], v[128:131], v[194:197], v[108:111]
	v_mfma_f32_16x16x32_bf16 v[104:107], v[136:139], v[194:197], v[104:107]
	v_mfma_f32_16x16x32_bf16 v[92:95], v[128:131], v[204:207], v[92:95]
	v_mfma_f32_16x16x32_bf16 v[88:91], v[136:139], v[204:207], v[88:91]
	v_mfma_f32_16x16x32_bf16 v[76:79], v[128:131], v[212:215], v[76:79]
	v_mfma_f32_16x16x32_bf16 v[72:75], v[136:139], v[212:215], v[72:75]
	v_mfma_f32_16x16x32_bf16 v[124:127], v[132:135], v[180:183], v[124:127]
	v_mfma_f32_16x16x32_bf16 v[120:123], v[140:143], v[180:183], v[120:123]
	v_mfma_f32_16x16x32_bf16 v[108:111], v[132:135], v[198:201], v[108:111]
	v_mfma_f32_16x16x32_bf16 v[104:107], v[140:143], v[198:201], v[104:107]
	v_mfma_f32_16x16x32_bf16 v[92:95], v[132:135], v[208:211], v[92:95]
	v_mfma_f32_16x16x32_bf16 v[88:91], v[140:143], v[208:211], v[88:91]
	v_mfma_f32_16x16x32_bf16 v[76:79], v[132:135], v[216:219], v[76:79]
	v_mfma_f32_16x16x32_bf16 v[72:75], v[140:143], v[216:219], v[72:75]
	s_setprio 0
	s_setprio 1
	v_mfma_f32_16x16x32_bf16 v[116:119], v[144:147], v[176:179], v[116:119]
	v_mfma_f32_16x16x32_bf16 v[112:115], v[168:171], v[176:179], v[112:115]
	v_mfma_f32_16x16x32_bf16 v[100:103], v[144:147], v[194:197], v[100:103]
	v_mfma_f32_16x16x32_bf16 v[96:99], v[168:171], v[194:197], v[96:99]
	v_mfma_f32_16x16x32_bf16 v[84:87], v[144:147], v[204:207], v[84:87]
	v_mfma_f32_16x16x32_bf16 v[80:83], v[168:171], v[204:207], v[80:83]
	v_mfma_f32_16x16x32_bf16 v[68:71], v[144:147], v[212:215], v[68:71]
	v_mfma_f32_16x16x32_bf16 v[64:67], v[168:171], v[212:215], v[64:67]
	v_mfma_f32_16x16x32_bf16 v[116:119], v[148:151], v[180:183], v[116:119]
	v_mfma_f32_16x16x32_bf16 v[112:115], v[172:175], v[180:183], v[112:115]
	v_mfma_f32_16x16x32_bf16 v[100:103], v[148:151], v[198:201], v[100:103]
	v_mfma_f32_16x16x32_bf16 v[96:99], v[172:175], v[198:201], v[96:99]
	v_mfma_f32_16x16x32_bf16 v[84:87], v[148:151], v[208:211], v[84:87]
	v_mfma_f32_16x16x32_bf16 v[80:83], v[172:175], v[208:211], v[80:83]
	v_mfma_f32_16x16x32_bf16 v[68:71], v[148:151], v[216:219], v[68:71]
	v_mfma_f32_16x16x32_bf16 v[64:67], v[172:175], v[216:219], v[64:67]
	s_setprio 0
	s_barrier
	s_add_i32 s22, s58, s42
	v_lshl_add_u64 v[184:185], v[184:185], 0, s[30:31]
	s_mov_b32 m0, s22
	ds_read_b128 v[176:179], v191 offset:49152
	ds_read_b128 v[180:183], v191 offset:50176
	ds_read_b128 v[194:197], v191 offset:51200
	ds_read_b128 v[198:201], v191 offset:52224
	ds_read_b128 v[204:207], v191 offset:53248
	ds_read_b128 v[208:211], v191 offset:54272
	ds_read_b128 v[212:215], v191 offset:55296
	ds_read_b128 v[216:219], v191 offset:56320
	global_load_lds_dwordx4 v[184:185], off
	s_add_i32 m0, s22, 0x2000
	s_add_u32 s22, s38, 0xb0080
	v_lshl_add_u64 v[184:185], v[220:221], 0, s[30:31]
	s_addc_u32 s23, s39, 0
	s_add_i32 s38, s59, s42
	global_load_lds_dwordx4 v[184:185], off
	v_lshl_add_u64 v[184:185], s[22:23], 0, v[154:155]
	s_mov_b32 m0, s38
	s_nop 0
	global_load_lds_dwordx4 v[184:185], off
	v_lshl_add_u64 v[184:185], s[22:23], 0, v[158:159]
	s_add_i32 m0, s38, 0x2000
	s_nop 0
	global_load_lds_dwordx4 v[184:185], off
	v_lshl_add_u64 v[184:185], v[222:223], 0, s[30:31]
	s_mov_b32 m0, s33
	s_nop 0
	global_load_lds_dwordx4 v[184:185], off
	v_lshl_add_u64 v[184:185], v[224:225], 0, s[30:31]
	s_mov_b32 m0, s48
	s_nop 0
	global_load_lds_dwordx4 v[184:185], off
	s_waitcnt vmcnt(8)
	s_waitcnt lgkmcnt(0)
	s_barrier
	s_setprio 1
	s_waitcnt lgkmcnt(0)
	v_mfma_f32_16x16x32_bf16 v[60:63], v[128:131], v[176:179], v[60:63]
	v_mfma_f32_16x16x32_bf16 v[56:59], v[136:139], v[176:179], v[56:59]
	v_mfma_f32_16x16x32_bf16 v[44:47], v[128:131], v[194:197], v[44:47]
	v_mfma_f32_16x16x32_bf16 v[40:43], v[136:139], v[194:197], v[40:43]
	v_mfma_f32_16x16x32_bf16 v[28:31], v[128:131], v[204:207], v[28:31]
	v_mfma_f32_16x16x32_bf16 v[24:27], v[136:139], v[204:207], v[24:27]
	v_mfma_f32_16x16x32_bf16 v[12:15], v[128:131], v[212:215], v[12:15]
	v_mfma_f32_16x16x32_bf16 v[8:11], v[136:139], v[212:215], v[8:11]
	v_mfma_f32_16x16x32_bf16 v[60:63], v[132:135], v[180:183], v[60:63]
	v_mfma_f32_16x16x32_bf16 v[56:59], v[140:143], v[180:183], v[56:59]
	v_mfma_f32_16x16x32_bf16 v[44:47], v[132:135], v[198:201], v[44:47]
	v_mfma_f32_16x16x32_bf16 v[40:43], v[140:143], v[198:201], v[40:43]
	v_mfma_f32_16x16x32_bf16 v[28:31], v[132:135], v[208:211], v[28:31]
	v_mfma_f32_16x16x32_bf16 v[24:27], v[140:143], v[208:211], v[24:27]
	v_mfma_f32_16x16x32_bf16 v[12:15], v[132:135], v[216:219], v[12:15]
	v_mfma_f32_16x16x32_bf16 v[8:11], v[140:143], v[216:219], v[8:11]
	s_setprio 0
	s_setprio 1
	v_mfma_f32_16x16x32_bf16 v[52:55], v[144:147], v[176:179], v[52:55]
	v_mfma_f32_16x16x32_bf16 v[48:51], v[168:171], v[176:179], v[48:51]
	v_mfma_f32_16x16x32_bf16 v[36:39], v[144:147], v[194:197], v[36:39]
	v_mfma_f32_16x16x32_bf16 v[32:35], v[168:171], v[194:197], v[32:35]
	v_mfma_f32_16x16x32_bf16 v[20:23], v[144:147], v[204:207], v[20:23]
	v_mfma_f32_16x16x32_bf16 v[16:19], v[168:171], v[204:207], v[16:19]
	v_mfma_f32_16x16x32_bf16 v[4:7], v[144:147], v[212:215], v[4:7]
	v_mfma_f32_16x16x32_bf16 v[0:3], v[168:171], v[212:215], v[0:3]
	v_mfma_f32_16x16x32_bf16 v[52:55], v[148:151], v[180:183], v[52:55]
	v_mfma_f32_16x16x32_bf16 v[48:51], v[172:175], v[180:183], v[48:51]
	v_mfma_f32_16x16x32_bf16 v[36:39], v[148:151], v[198:201], v[36:39]
	v_mfma_f32_16x16x32_bf16 v[32:35], v[172:175], v[198:201], v[32:35]
	v_mfma_f32_16x16x32_bf16 v[20:23], v[148:151], v[208:211], v[20:23]
	v_mfma_f32_16x16x32_bf16 v[16:19], v[172:175], v[208:211], v[16:19]
	v_mfma_f32_16x16x32_bf16 v[4:7], v[148:151], v[216:219], v[4:7]
	v_mfma_f32_16x16x32_bf16 v[0:3], v[172:175], v[216:219], v[0:3]
	s_setprio 0
	s_add_i32 s57, s57, 2
	s_add_u32 s55, s55, 0x100
	s_addc_u32 s56, s56, 0
	s_cmp_gt_u32 s57, 41
	s_mov_b64 s[22:23], s[4:5]
	s_cbranch_scc1 .Lkexit_3
	s_barrier
	s_branch .LBB0_559
.Lkexit_3:
	s_and_b64 vcc, exec, s[34:35]
	s_cbranch_vccz .LBB0_562
	s_barrier

.LBB0_643:
	ds_read_b128 v[128:131], v191
	ds_read_b128 v[132:135], v191 offset:1024
	ds_read_b128 v[156:159], v191 offset:2048
	ds_read_b128 v[160:163], v191 offset:3072
	ds_read_b128 v[164:167], v192
	ds_read_b128 v[168:171], v192 offset:1024
	ds_read_b128 v[172:175], v192 offset:2048
	ds_read_b128 v[176:179], v192 offset:3072
	s_add_u32 s4, s22, 0xfffc0080
	s_addc_u32 s5, s23, -1
	s_cmp_eq_u32 s63, 12
	s_cselect_b32 s47, s13, s5
	s_cselect_b32 s46, s17, s4
	s_cselect_b32 s5, s33, s62
	s_cselect_b32 s4, s39, s41
	v_lshl_add_u64 v[224:225], s[22:23], 0, v[148:149]
	s_add_i32 m0, s49, 0xc000
	ds_read_b128 v[180:183], v193
	ds_read_b128 v[184:187], v193 offset:1024
	ds_read_b128 v[198:201], v193 offset:2048
	ds_read_b128 v[204:207], v193 offset:3072
	ds_read_b128 v[208:211], v193 offset:4096
	ds_read_b128 v[212:215], v193 offset:5120
	ds_read_b128 v[216:219], v193 offset:6144
	ds_read_b128 v[220:223], v193 offset:7168
	global_load_lds_dwordx4 v[224:225], off
	v_lshl_add_u64 v[224:225], s[22:23], 0, v[150:151]
	s_add_i32 m0, s49, 0xe000
	s_nop 0
	global_load_lds_dwordx4 v[224:225], off
	s_waitcnt vmcnt(8)
	s_waitcnt lgkmcnt(0)
	s_barrier
	s_setprio 1
	s_waitcnt lgkmcnt(0)
	v_mfma_f32_16x16x32_bf16 v[124:127], v[128:131], v[180:183], v[124:127]
	v_mfma_f32_16x16x32_bf16 v[120:123], v[156:159], v[180:183], v[120:123]
	v_mfma_f32_16x16x32_bf16 v[108:111], v[128:131], v[198:201], v[108:111]
	v_mfma_f32_16x16x32_bf16 v[104:107], v[156:159], v[198:201], v[104:107]
	v_mfma_f32_16x16x32_bf16 v[92:95], v[128:131], v[208:211], v[92:95]
	v_mfma_f32_16x16x32_bf16 v[88:91], v[156:159], v[208:211], v[88:91]
	v_mfma_f32_16x16x32_bf16 v[76:79], v[128:131], v[216:219], v[76:79]
	v_mfma_f32_16x16x32_bf16 v[72:75], v[156:159], v[216:219], v[72:75]
	v_mfma_f32_16x16x32_bf16 v[124:127], v[132:135], v[184:187], v[124:127]
	v_mfma_f32_16x16x32_bf16 v[120:123], v[160:163], v[184:187], v[120:123]
	v_mfma_f32_16x16x32_bf16 v[108:111], v[132:135], v[204:207], v[108:111]
	v_mfma_f32_16x16x32_bf16 v[104:107], v[160:163], v[204:207], v[104:107]
	v_mfma_f32_16x16x32_bf16 v[92:95], v[132:135], v[212:215], v[92:95]
	v_mfma_f32_16x16x32_bf16 v[88:91], v[160:163], v[212:215], v[88:91]
	v_mfma_f32_16x16x32_bf16 v[76:79], v[132:135], v[220:223], v[76:79]
	v_mfma_f32_16x16x32_bf16 v[72:75], v[160:163], v[220:223], v[72:75]
	s_setprio 0
	s_setprio 1
	v_mfma_f32_16x16x32_bf16 v[116:119], v[164:167], v[180:183], v[116:119]
	v_mfma_f32_16x16x32_bf16 v[112:115], v[172:175], v[180:183], v[112:115]
	v_mfma_f32_16x16x32_bf16 v[100:103], v[164:167], v[198:201], v[100:103]
	v_mfma_f32_16x16x32_bf16 v[96:99], v[172:175], v[198:201], v[96:99]
	v_mfma_f32_16x16x32_bf16 v[84:87], v[164:167], v[208:211], v[84:87]
	v_mfma_f32_16x16x32_bf16 v[80:83], v[172:175], v[208:211], v[80:83]
	v_mfma_f32_16x16x32_bf16 v[68:71], v[164:167], v[216:219], v[68:71]
	v_mfma_f32_16x16x32_bf16 v[64:67], v[172:175], v[216:219], v[64:67]
	v_mfma_f32_16x16x32_bf16 v[116:119], v[168:171], v[184:187], v[116:119]
	v_mfma_f32_16x16x32_bf16 v[112:115], v[176:179], v[184:187], v[112:115]
	v_mfma_f32_16x16x32_bf16 v[100:103], v[168:171], v[204:207], v[100:103]
	v_mfma_f32_16x16x32_bf16 v[96:99], v[176:179], v[204:207], v[96:99]
	v_mfma_f32_16x16x32_bf16 v[84:87], v[168:171], v[212:215], v[84:87]
	v_mfma_f32_16x16x32_bf16 v[80:83], v[176:179], v[212:215], v[80:83]
	v_mfma_f32_16x16x32_bf16 v[68:71], v[168:171], v[220:223], v[68:71]
	v_mfma_f32_16x16x32_bf16 v[64:67], v[176:179], v[220:223], v[64:67]
	s_setprio 0
	s_barrier
	s_add_i32 s64, s59, s48
	v_lshl_add_u64 v[224:225], s[4:5], 0, v[138:139]
	s_mov_b32 m0, s64
	ds_read_b128 v[180:183], v193 offset:16384
	ds_read_b128 v[184:187], v193 offset:17408
	ds_read_b128 v[198:201], v193 offset:18432
	ds_read_b128 v[204:207], v193 offset:19456
	ds_read_b128 v[208:211], v193 offset:20480
	ds_read_b128 v[212:215], v193 offset:21504
	ds_read_b128 v[216:219], v193 offset:22528
	ds_read_b128 v[220:223], v193 offset:23552
	global_load_lds_dwordx4 v[224:225], off
	s_add_i32 m0, s64, 0x2000
	s_add_u32 s64, s4, 0x40000
	v_lshl_add_u64 v[226:227], s[4:5], 0, v[142:143]
	s_addc_u32 s65, s5, 0
	s_add_i32 s66, s60, s48
	global_load_lds_dwordx4 v[226:227], off
	v_lshl_add_u64 v[228:229], s[64:65], 0, v[138:139]
	s_mov_b32 m0, s66
	v_lshl_add_u64 v[230:231], s[46:47], 0, v[140:141]
	global_load_lds_dwordx4 v[228:229], off
	v_lshl_add_u64 v[228:229], s[64:65], 0, v[142:143]
	s_add_i32 m0, s66, 0x2000
	s_nop 0
	global_load_lds_dwordx4 v[228:229], off
	v_lshl_add_u64 v[228:229], s[46:47], 0, v[136:137]
	s_mov_b32 m0, s49
	s_nop 0
	global_load_lds_dwordx4 v[228:229], off
	s_mov_b32 m0, s50
	s_nop 0
	global_load_lds_dwordx4 v[230:231], off
	s_waitcnt vmcnt(8)
	s_waitcnt lgkmcnt(0)
	s_barrier
	s_setprio 1
	s_waitcnt lgkmcnt(0)
	v_mfma_f32_16x16x32_bf16 v[60:63], v[128:131], v[180:183], v[60:63]
	v_mfma_f32_16x16x32_bf16 v[56:59], v[156:159], v[180:183], v[56:59]
	v_mfma_f32_16x16x32_bf16 v[44:47], v[128:131], v[198:201], v[44:47]
	v_mfma_f32_16x16x32_bf16 v[40:43], v[156:159], v[198:201], v[40:43]
	v_mfma_f32_16x16x32_bf16 v[28:31], v[128:131], v[208:211], v[28:31]
	v_mfma_f32_16x16x32_bf16 v[24:27], v[156:159], v[208:211], v[24:27]
	v_mfma_f32_16x16x32_bf16 v[12:15], v[128:131], v[216:219], v[12:15]
	v_mfma_f32_16x16x32_bf16 v[8:11], v[156:159], v[216:219], v[8:11]
	v_mfma_f32_16x16x32_bf16 v[60:63], v[132:135], v[184:187], v[60:63]
	v_mfma_f32_16x16x32_bf16 v[56:59], v[160:163], v[184:187], v[56:59]
	v_mfma_f32_16x16x32_bf16 v[44:47], v[132:135], v[204:207], v[44:47]
	v_mfma_f32_16x16x32_bf16 v[40:43], v[160:163], v[204:207], v[40:43]
	v_mfma_f32_16x16x32_bf16 v[28:31], v[132:135], v[212:215], v[28:31]
	v_mfma_f32_16x16x32_bf16 v[24:27], v[160:163], v[212:215], v[24:27]
	v_mfma_f32_16x16x32_bf16 v[12:15], v[132:135], v[220:223], v[12:15]
	v_mfma_f32_16x16x32_bf16 v[8:11], v[160:163], v[220:223], v[8:11]
	s_setprio 0
	s_setprio 1
	v_mfma_f32_16x16x32_bf16 v[52:55], v[164:167], v[180:183], v[52:55]
	v_mfma_f32_16x16x32_bf16 v[48:51], v[172:175], v[180:183], v[48:51]
	v_mfma_f32_16x16x32_bf16 v[36:39], v[164:167], v[198:201], v[36:39]
	v_mfma_f32_16x16x32_bf16 v[32:35], v[172:175], v[198:201], v[32:35]
	v_mfma_f32_16x16x32_bf16 v[20:23], v[164:167], v[208:211], v[20:23]
	v_mfma_f32_16x16x32_bf16 v[16:19], v[172:175], v[208:211], v[16:19]
	v_mfma_f32_16x16x32_bf16 v[4:7], v[164:167], v[216:219], v[4:7]
	v_mfma_f32_16x16x32_bf16 v[0:3], v[172:175], v[216:219], v[0:3]
	v_mfma_f32_16x16x32_bf16 v[52:55], v[168:171], v[184:187], v[52:55]
	v_mfma_f32_16x16x32_bf16 v[48:51], v[176:179], v[184:187], v[48:51]
	v_mfma_f32_16x16x32_bf16 v[36:39], v[168:171], v[204:207], v[36:39]
	v_mfma_f32_16x16x32_bf16 v[32:35], v[176:179], v[204:207], v[32:35]
	v_mfma_f32_16x16x32_bf16 v[20:23], v[168:171], v[212:215], v[20:23]
	v_mfma_f32_16x16x32_bf16 v[16:19], v[176:179], v[212:215], v[16:19]
	v_mfma_f32_16x16x32_bf16 v[4:7], v[168:171], v[220:223], v[4:7]
	v_mfma_f32_16x16x32_bf16 v[0:3], v[176:179], v[220:223], v[0:3]
	s_setprio 0
	s_barrier
	s_add_i32 s64, 0, 0x18000
	v_add_u32_e32 v144, s64, v189
	s_add_i32 s65, 0, 0x1c000
	ds_read_b128 v[128:131], v144
	ds_read_b128 v[132:135], v144 offset:1024
	ds_read_b128 v[156:159], v144 offset:2048
	ds_read_b128 v[160:163], v144 offset:3072
	v_add_u32_e32 v144, s65, v189
	ds_read_b128 v[164:167], v144
	ds_read_b128 v[168:171], v144 offset:1024
	ds_read_b128 v[172:175], v144 offset:2048
	ds_read_b128 v[176:179], v144 offset:3072
	s_add_u32 s46, s46, 0x40000
	s_addc_u32 s47, s47, 0
	s_mov_b32 m0, s51
	v_lshl_add_u64 v[232:233], s[46:47], 0, v[136:137]
	ds_read_b128 v[180:183], v193 offset:32768
	ds_read_b128 v[184:187], v193 offset:33792
	ds_read_b128 v[198:201], v193 offset:34816
	ds_read_b128 v[204:207], v193 offset:35840
	ds_read_b128 v[208:211], v193 offset:36864
	ds_read_b128 v[212:215], v193 offset:37888
	ds_read_b128 v[216:219], v193 offset:38912
	ds_read_b128 v[220:223], v193 offset:39936
	global_load_lds_dwordx4 v[232:233], off
	v_lshl_add_u64 v[232:233], s[46:47], 0, v[140:141]
	s_mov_b32 m0, s52
	s_nop 0
	global_load_lds_dwordx4 v[232:233], off
	s_waitcnt vmcnt(8)
	s_waitcnt lgkmcnt(0)
	s_barrier
	s_setprio 1
	s_waitcnt lgkmcnt(0)
	v_mfma_f32_16x16x32_bf16 v[124:127], v[128:131], v[180:183], v[124:127]
	v_mfma_f32_16x16x32_bf16 v[120:123], v[156:159], v[180:183], v[120:123]
	v_mfma_f32_16x16x32_bf16 v[108:111], v[128:131], v[198:201], v[108:111]
	v_mfma_f32_16x16x32_bf16 v[104:107], v[156:159], v[198:201], v[104:107]
	v_mfma_f32_16x16x32_bf16 v[92:95], v[128:131], v[208:211], v[92:95]
	v_mfma_f32_16x16x32_bf16 v[88:91], v[156:159], v[208:211], v[88:91]
	v_mfma_f32_16x16x32_bf16 v[76:79], v[128:131], v[216:219], v[76:79]
	v_mfma_f32_16x16x32_bf16 v[72:75], v[156:159], v[216:219], v[72:75]
	v_mfma_f32_16x16x32_bf16 v[124:127], v[132:135], v[184:187], v[124:127]
	v_mfma_f32_16x16x32_bf16 v[120:123], v[160:163], v[184:187], v[120:123]
	v_mfma_f32_16x16x32_bf16 v[108:111], v[132:135], v[204:207], v[108:111]
	v_mfma_f32_16x16x32_bf16 v[104:107], v[160:163], v[204:207], v[104:107]
	v_mfma_f32_16x16x32_bf16 v[92:95], v[132:135], v[212:215], v[92:95]
	v_mfma_f32_16x16x32_bf16 v[88:91], v[160:163], v[212:215], v[88:91]
	v_mfma_f32_16x16x32_bf16 v[76:79], v[132:135], v[220:223], v[76:79]
	v_mfma_f32_16x16x32_bf16 v[72:75], v[160:163], v[220:223], v[72:75]
	s_setprio 0
	s_setprio 1
	v_mfma_f32_16x16x32_bf16 v[116:119], v[164:167], v[180:183], v[116:119]
	v_mfma_f32_16x16x32_bf16 v[112:115], v[172:175], v[180:183], v[112:115]
	v_mfma_f32_16x16x32_bf16 v[100:103], v[164:167], v[198:201], v[100:103]
	v_mfma_f32_16x16x32_bf16 v[96:99], v[172:175], v[198:201], v[96:99]
	v_mfma_f32_16x16x32_bf16 v[84:87], v[164:167], v[208:211], v[84:87]
	v_mfma_f32_16x16x32_bf16 v[80:83], v[172:175], v[208:211], v[80:83]
	v_mfma_f32_16x16x32_bf16 v[68:71], v[164:167], v[216:219], v[68:71]
	v_mfma_f32_16x16x32_bf16 v[64:67], v[172:175], v[216:219], v[64:67]
	v_mfma_f32_16x16x32_bf16 v[116:119], v[168:171], v[184:187], v[116:119]
	v_mfma_f32_16x16x32_bf16 v[112:115], v[176:179], v[184:187], v[112:115]
	v_mfma_f32_16x16x32_bf16 v[100:103], v[168:171], v[204:207], v[100:103]
	v_mfma_f32_16x16x32_bf16 v[96:99], v[176:179], v[204:207], v[96:99]
	v_mfma_f32_16x16x32_bf16 v[84:87], v[168:171], v[212:215], v[84:87]
	v_mfma_f32_16x16x32_bf16 v[80:83], v[176:179], v[212:215], v[80:83]
	v_mfma_f32_16x16x32_bf16 v[68:71], v[168:171], v[220:223], v[68:71]
	v_mfma_f32_16x16x32_bf16 v[64:67], v[176:179], v[220:223], v[64:67]
	s_setprio 0
	s_barrier
	s_add_i32 s46, s64, s48
	v_lshl_add_u64 v[224:225], v[224:225], 0, s[30:31]
	s_mov_b32 m0, s46
	ds_read_b128 v[180:183], v193 offset:49152
	ds_read_b128 v[184:187], v193 offset:50176
	ds_read_b128 v[198:201], v193 offset:51200
	ds_read_b128 v[204:207], v193 offset:52224
	ds_read_b128 v[208:211], v193 offset:53248
	ds_read_b128 v[212:215], v193 offset:54272
	ds_read_b128 v[216:219], v193 offset:55296
	ds_read_b128 v[220:223], v193 offset:56320
	global_load_lds_dwordx4 v[224:225], off
	s_add_i32 m0, s46, 0x2000
	s_add_u32 s4, s4, 0x40080
	v_lshl_add_u64 v[224:225], v[226:227], 0, s[30:31]
	s_addc_u32 s5, s5, 0
	s_add_i32 s46, s65, s48
	global_load_lds_dwordx4 v[224:225], off
	v_lshl_add_u64 v[224:225], s[4:5], 0, v[138:139]
	s_mov_b32 m0, s46
	s_nop 0
	global_load_lds_dwordx4 v[224:225], off
	v_lshl_add_u64 v[224:225], s[4:5], 0, v[142:143]
	s_add_i32 m0, s46, 0x2000
	s_nop 0
	global_load_lds_dwordx4 v[224:225], off
	v_lshl_add_u64 v[224:225], v[228:229], 0, s[30:31]
	s_mov_b32 m0, s56
	s_nop 0
	global_load_lds_dwordx4 v[224:225], off
	v_lshl_add_u64 v[224:225], v[230:231], 0, s[30:31]
	s_mov_b32 m0, s57
	s_nop 0
	global_load_lds_dwordx4 v[224:225], off
	s_waitcnt vmcnt(8)
	s_waitcnt lgkmcnt(0)
	s_barrier
	s_setprio 1
	s_waitcnt lgkmcnt(0)
	v_mfma_f32_16x16x32_bf16 v[60:63], v[128:131], v[180:183], v[60:63]
	v_mfma_f32_16x16x32_bf16 v[56:59], v[156:159], v[180:183], v[56:59]
	v_mfma_f32_16x16x32_bf16 v[44:47], v[128:131], v[198:201], v[44:47]
	v_mfma_f32_16x16x32_bf16 v[40:43], v[156:159], v[198:201], v[40:43]
	v_mfma_f32_16x16x32_bf16 v[28:31], v[128:131], v[208:211], v[28:31]
	v_mfma_f32_16x16x32_bf16 v[24:27], v[156:159], v[208:211], v[24:27]
	v_mfma_f32_16x16x32_bf16 v[12:15], v[128:131], v[216:219], v[12:15]
	v_mfma_f32_16x16x32_bf16 v[8:11], v[156:159], v[216:219], v[8:11]
	v_mfma_f32_16x16x32_bf16 v[60:63], v[132:135], v[184:187], v[60:63]
	v_mfma_f32_16x16x32_bf16 v[56:59], v[160:163], v[184:187], v[56:59]
	v_mfma_f32_16x16x32_bf16 v[44:47], v[132:135], v[204:207], v[44:47]
	v_mfma_f32_16x16x32_bf16 v[40:43], v[160:163], v[204:207], v[40:43]
	v_mfma_f32_16x16x32_bf16 v[28:31], v[132:135], v[212:215], v[28:31]
	v_mfma_f32_16x16x32_bf16 v[24:27], v[160:163], v[212:215], v[24:27]
	v_mfma_f32_16x16x32_bf16 v[12:15], v[132:135], v[220:223], v[12:15]
	v_mfma_f32_16x16x32_bf16 v[8:11], v[160:163], v[220:223], v[8:11]
	s_setprio 0
	s_setprio 1
	v_mfma_f32_16x16x32_bf16 v[52:55], v[164:167], v[180:183], v[52:55]
	v_mfma_f32_16x16x32_bf16 v[48:51], v[172:175], v[180:183], v[48:51]
	v_mfma_f32_16x16x32_bf16 v[36:39], v[164:167], v[198:201], v[36:39]
	v_mfma_f32_16x16x32_bf16 v[32:35], v[172:175], v[198:201], v[32:35]
	v_mfma_f32_16x16x32_bf16 v[20:23], v[164:167], v[208:211], v[20:23]
	v_mfma_f32_16x16x32_bf16 v[16:19], v[172:175], v[208:211], v[16:19]
	v_mfma_f32_16x16x32_bf16 v[4:7], v[164:167], v[216:219], v[4:7]
	v_mfma_f32_16x16x32_bf16 v[0:3], v[172:175], v[216:219], v[0:3]
	v_mfma_f32_16x16x32_bf16 v[52:55], v[168:171], v[184:187], v[52:55]
	v_mfma_f32_16x16x32_bf16 v[48:51], v[176:179], v[184:187], v[48:51]
	v_mfma_f32_16x16x32_bf16 v[36:39], v[168:171], v[204:207], v[36:39]
	v_mfma_f32_16x16x32_bf16 v[32:35], v[176:179], v[204:207], v[32:35]
	v_mfma_f32_16x16x32_bf16 v[20:23], v[168:171], v[212:215], v[20:23]
	v_mfma_f32_16x16x32_bf16 v[16:19], v[176:179], v[212:215], v[16:19]
	v_mfma_f32_16x16x32_bf16 v[4:7], v[168:171], v[220:223], v[4:7]
	v_mfma_f32_16x16x32_bf16 v[0:3], v[176:179], v[220:223], v[0:3]
	s_setprio 0
	s_add_i32 s63, s63, 2
	s_add_u32 s22, s22, 0x100
	s_addc_u32 s23, s23, 0
	s_add_u32 s41, s41, 0x100
	s_addc_u32 s62, s62, 0
	s_cmp_gt_u32 s63, 13
	s_cbranch_scc1 .Lkexit_4
	s_barrier
	s_branch .LBB0_643

.LBB0_966:
	ds_read_b128 v[128:131], v189
	ds_read_b128 v[132:135], v189 offset:1024
	ds_read_b128 v[136:139], v189 offset:2048
	ds_read_b128 v[140:143], v189 offset:3072
	ds_read_b128 v[144:147], v190
	ds_read_b128 v[148:151], v190 offset:1024
	ds_read_b128 v[168:171], v190 offset:2048
	ds_read_b128 v[172:175], v190 offset:3072
	s_add_u32 s4, s22, 0xfffc0080
	s_addc_u32 s5, s23, -1
	s_cmp_eq_u32 s58, 12
	s_cselect_b32 s43, s35, s5
	s_cselect_b32 s42, s41, s4
	s_cselect_b32 s5, s31, s57
	s_cselect_b32 s4, s55, s56
	v_lshl_add_u64 v[184:185], s[22:23], 0, v[160:161]
	s_add_i32 m0, s46, 0xc000
	ds_read_b128 v[176:179], v191
	ds_read_b128 v[180:183], v191 offset:1024
	ds_read_b128 v[192:195], v191 offset:2048
	ds_read_b128 v[198:201], v191 offset:3072
	ds_read_b128 v[204:207], v191 offset:4096
	ds_read_b128 v[208:211], v191 offset:5120
	ds_read_b128 v[212:215], v191 offset:6144
	ds_read_b128 v[216:219], v191 offset:7168
	global_load_lds_dwordx4 v[184:185], off
	v_lshl_add_u64 v[184:185], s[22:23], 0, v[162:163]
	s_add_i32 m0, s46, 0xe000
	s_nop 0
	global_load_lds_dwordx4 v[184:185], off
	s_waitcnt vmcnt(8)
	s_waitcnt lgkmcnt(0)
	s_barrier
	s_setprio 1
	s_waitcnt lgkmcnt(0)
	v_mfma_f32_16x16x32_bf16 v[124:127], v[128:131], v[176:179], v[124:127]
	v_mfma_f32_16x16x32_bf16 v[120:123], v[136:139], v[176:179], v[120:123]
	v_mfma_f32_16x16x32_bf16 v[108:111], v[128:131], v[192:195], v[108:111]
	v_mfma_f32_16x16x32_bf16 v[104:107], v[136:139], v[192:195], v[104:107]
	v_mfma_f32_16x16x32_bf16 v[92:95], v[128:131], v[204:207], v[92:95]
	v_mfma_f32_16x16x32_bf16 v[88:91], v[136:139], v[204:207], v[88:91]
	v_mfma_f32_16x16x32_bf16 v[76:79], v[128:131], v[212:215], v[76:79]
	v_mfma_f32_16x16x32_bf16 v[72:75], v[136:139], v[212:215], v[72:75]
	v_mfma_f32_16x16x32_bf16 v[124:127], v[132:135], v[180:183], v[124:127]
	v_mfma_f32_16x16x32_bf16 v[120:123], v[140:143], v[180:183], v[120:123]
	v_mfma_f32_16x16x32_bf16 v[108:111], v[132:135], v[198:201], v[108:111]
	v_mfma_f32_16x16x32_bf16 v[104:107], v[140:143], v[198:201], v[104:107]
	v_mfma_f32_16x16x32_bf16 v[92:95], v[132:135], v[208:211], v[92:95]
	v_mfma_f32_16x16x32_bf16 v[88:91], v[140:143], v[208:211], v[88:91]
	v_mfma_f32_16x16x32_bf16 v[76:79], v[132:135], v[216:219], v[76:79]
	v_mfma_f32_16x16x32_bf16 v[72:75], v[140:143], v[216:219], v[72:75]
	s_setprio 0
	s_setprio 1
	v_mfma_f32_16x16x32_bf16 v[116:119], v[144:147], v[176:179], v[116:119]
	v_mfma_f32_16x16x32_bf16 v[112:115], v[168:171], v[176:179], v[112:115]
	v_mfma_f32_16x16x32_bf16 v[100:103], v[144:147], v[192:195], v[100:103]
	v_mfma_f32_16x16x32_bf16 v[96:99], v[168:171], v[192:195], v[96:99]
	v_mfma_f32_16x16x32_bf16 v[84:87], v[144:147], v[204:207], v[84:87]
	v_mfma_f32_16x16x32_bf16 v[80:83], v[168:171], v[204:207], v[80:83]
	v_mfma_f32_16x16x32_bf16 v[68:71], v[144:147], v[212:215], v[68:71]
	v_mfma_f32_16x16x32_bf16 v[64:67], v[168:171], v[212:215], v[64:67]
	v_mfma_f32_16x16x32_bf16 v[116:119], v[148:151], v[180:183], v[116:119]
	v_mfma_f32_16x16x32_bf16 v[112:115], v[172:175], v[180:183], v[112:115]
	v_mfma_f32_16x16x32_bf16 v[100:103], v[148:151], v[198:201], v[100:103]
	v_mfma_f32_16x16x32_bf16 v[96:99], v[172:175], v[198:201], v[96:99]
	v_mfma_f32_16x16x32_bf16 v[84:87], v[148:151], v[208:211], v[84:87]
	v_mfma_f32_16x16x32_bf16 v[80:83], v[172:175], v[208:211], v[80:83]
	v_mfma_f32_16x16x32_bf16 v[68:71], v[148:151], v[216:219], v[68:71]
	v_mfma_f32_16x16x32_bf16 v[64:67], v[172:175], v[216:219], v[64:67]
	s_setprio 0
	s_barrier
	s_add_i32 s59, s52, s45
	v_lshl_add_u64 v[184:185], s[4:5], 0, v[154:155]
	s_mov_b32 m0, s59
	ds_read_b128 v[176:179], v191 offset:16384
	ds_read_b128 v[180:183], v191 offset:17408
	ds_read_b128 v[192:195], v191 offset:18432
	ds_read_b128 v[198:201], v191 offset:19456
	ds_read_b128 v[204:207], v191 offset:20480
	ds_read_b128 v[208:211], v191 offset:21504
	ds_read_b128 v[212:215], v191 offset:22528
	ds_read_b128 v[216:219], v191 offset:23552
	global_load_lds_dwordx4 v[184:185], off
	s_add_i32 m0, s59, 0x2000
	s_add_u32 s60, s4, 0x40000
	v_lshl_add_u64 v[220:221], s[4:5], 0, v[158:159]
	s_addc_u32 s61, s5, 0
	s_add_i32 s59, s53, s45
	global_load_lds_dwordx4 v[220:221], off
	v_lshl_add_u64 v[222:223], s[60:61], 0, v[154:155]
	s_mov_b32 m0, s59
	v_lshl_add_u64 v[224:225], s[42:43], 0, v[156:157]
	global_load_lds_dwordx4 v[222:223], off
	v_lshl_add_u64 v[222:223], s[60:61], 0, v[158:159]
	s_add_i32 m0, s59, 0x2000
	s_nop 0
	global_load_lds_dwordx4 v[222:223], off
	v_lshl_add_u64 v[222:223], s[42:43], 0, v[152:153]
	s_mov_b32 m0, s46
	s_nop 0
	global_load_lds_dwordx4 v[222:223], off
	s_mov_b32 m0, s33
	s_nop 0
	global_load_lds_dwordx4 v[224:225], off
	s_waitcnt vmcnt(8)
	s_waitcnt lgkmcnt(0)
	s_barrier
	s_setprio 1
	s_waitcnt lgkmcnt(0)
	v_mfma_f32_16x16x32_bf16 v[60:63], v[128:131], v[176:179], v[60:63]
	v_mfma_f32_16x16x32_bf16 v[56:59], v[136:139], v[176:179], v[56:59]
	v_mfma_f32_16x16x32_bf16 v[44:47], v[128:131], v[192:195], v[44:47]
	v_mfma_f32_16x16x32_bf16 v[40:43], v[136:139], v[192:195], v[40:43]
	v_mfma_f32_16x16x32_bf16 v[28:31], v[128:131], v[204:207], v[28:31]
	v_mfma_f32_16x16x32_bf16 v[24:27], v[136:139], v[204:207], v[24:27]
	v_mfma_f32_16x16x32_bf16 v[12:15], v[128:131], v[212:215], v[12:15]
	v_mfma_f32_16x16x32_bf16 v[8:11], v[136:139], v[212:215], v[8:11]
	v_mfma_f32_16x16x32_bf16 v[60:63], v[132:135], v[180:183], v[60:63]
	v_mfma_f32_16x16x32_bf16 v[56:59], v[140:143], v[180:183], v[56:59]
	v_mfma_f32_16x16x32_bf16 v[44:47], v[132:135], v[198:201], v[44:47]
	v_mfma_f32_16x16x32_bf16 v[40:43], v[140:143], v[198:201], v[40:43]
	v_mfma_f32_16x16x32_bf16 v[28:31], v[132:135], v[208:211], v[28:31]
	v_mfma_f32_16x16x32_bf16 v[24:27], v[140:143], v[208:211], v[24:27]
	v_mfma_f32_16x16x32_bf16 v[12:15], v[132:135], v[216:219], v[12:15]
	v_mfma_f32_16x16x32_bf16 v[8:11], v[140:143], v[216:219], v[8:11]
	s_setprio 0
	s_setprio 1
	v_mfma_f32_16x16x32_bf16 v[52:55], v[144:147], v[176:179], v[52:55]
	v_mfma_f32_16x16x32_bf16 v[48:51], v[168:171], v[176:179], v[48:51]
	v_mfma_f32_16x16x32_bf16 v[36:39], v[144:147], v[192:195], v[36:39]
	v_mfma_f32_16x16x32_bf16 v[32:35], v[168:171], v[192:195], v[32:35]
	v_mfma_f32_16x16x32_bf16 v[20:23], v[144:147], v[204:207], v[20:23]
	v_mfma_f32_16x16x32_bf16 v[16:19], v[168:171], v[204:207], v[16:19]
	v_mfma_f32_16x16x32_bf16 v[4:7], v[144:147], v[212:215], v[4:7]
	v_mfma_f32_16x16x32_bf16 v[0:3], v[168:171], v[212:215], v[0:3]
	v_mfma_f32_16x16x32_bf16 v[52:55], v[148:151], v[180:183], v[52:55]
	v_mfma_f32_16x16x32_bf16 v[48:51], v[172:175], v[180:183], v[48:51]
	v_mfma_f32_16x16x32_bf16 v[36:39], v[148:151], v[198:201], v[36:39]
	v_mfma_f32_16x16x32_bf16 v[32:35], v[172:175], v[198:201], v[32:35]
	v_mfma_f32_16x16x32_bf16 v[20:23], v[148:151], v[208:211], v[20:23]
	v_mfma_f32_16x16x32_bf16 v[16:19], v[172:175], v[208:211], v[16:19]
	v_mfma_f32_16x16x32_bf16 v[4:7], v[148:151], v[216:219], v[4:7]
	v_mfma_f32_16x16x32_bf16 v[0:3], v[172:175], v[216:219], v[0:3]
	s_setprio 0
	s_barrier
	s_add_i32 s59, 0, 0x18000
	s_add_i32 s60, 0, 0x1c000
	v_add_u32_e32 v140, s59, v187
	v_add_u32_e32 v172, s60, v187
	ds_read_b128 v[128:131], v140
	ds_read_b128 v[132:135], v140 offset:1024
	ds_read_b128 v[136:139], v140 offset:2048
	ds_read_b128 v[140:143], v140 offset:3072
	ds_read_b128 v[144:147], v172
	ds_read_b128 v[148:151], v172 offset:1024
	ds_read_b128 v[168:171], v172 offset:2048
	ds_read_b128 v[172:175], v172 offset:3072
	s_add_u32 s42, s42, 0x40000
	s_addc_u32 s43, s43, 0
	s_mov_b32 m0, s47
	v_lshl_add_u64 v[226:227], s[42:43], 0, v[152:153]
	ds_read_b128 v[176:179], v191 offset:32768
	ds_read_b128 v[180:183], v191 offset:33792
	ds_read_b128 v[192:195], v191 offset:34816
	ds_read_b128 v[198:201], v191 offset:35840
	ds_read_b128 v[204:207], v191 offset:36864
	ds_read_b128 v[208:211], v191 offset:37888
	ds_read_b128 v[212:215], v191 offset:38912
	ds_read_b128 v[216:219], v191 offset:39936
	global_load_lds_dwordx4 v[226:227], off
	v_lshl_add_u64 v[226:227], s[42:43], 0, v[156:157]
	s_mov_b32 m0, s48
	s_nop 0
	global_load_lds_dwordx4 v[226:227], off
	s_waitcnt vmcnt(8)
	s_waitcnt lgkmcnt(0)
	s_barrier
	s_setprio 1
	s_waitcnt lgkmcnt(0)
	v_mfma_f32_16x16x32_bf16 v[124:127], v[128:131], v[176:179], v[124:127]
	v_mfma_f32_16x16x32_bf16 v[120:123], v[136:139], v[176:179], v[120:123]
	v_mfma_f32_16x16x32_bf16 v[108:111], v[128:131], v[192:195], v[108:111]
	v_mfma_f32_16x16x32_bf16 v[104:107], v[136:139], v[192:195], v[104:107]
	v_mfma_f32_16x16x32_bf16 v[92:95], v[128:131], v[204:207], v[92:95]
	v_mfma_f32_16x16x32_bf16 v[88:91], v[136:139], v[204:207], v[88:91]
	v_mfma_f32_16x16x32_bf16 v[76:79], v[128:131], v[212:215], v[76:79]
	v_mfma_f32_16x16x32_bf16 v[72:75], v[136:139], v[212:215], v[72:75]
	v_mfma_f32_16x16x32_bf16 v[124:127], v[132:135], v[180:183], v[124:127]
	v_mfma_f32_16x16x32_bf16 v[120:123], v[140:143], v[180:183], v[120:123]
	v_mfma_f32_16x16x32_bf16 v[108:111], v[132:135], v[198:201], v[108:111]
	v_mfma_f32_16x16x32_bf16 v[104:107], v[140:143], v[198:201], v[104:107]
	v_mfma_f32_16x16x32_bf16 v[92:95], v[132:135], v[208:211], v[92:95]
	v_mfma_f32_16x16x32_bf16 v[88:91], v[140:143], v[208:211], v[88:91]
	v_mfma_f32_16x16x32_bf16 v[76:79], v[132:135], v[216:219], v[76:79]
	v_mfma_f32_16x16x32_bf16 v[72:75], v[140:143], v[216:219], v[72:75]
	s_setprio 0
	s_setprio 1
	v_mfma_f32_16x16x32_bf16 v[116:119], v[144:147], v[176:179], v[116:119]
	v_mfma_f32_16x16x32_bf16 v[112:115], v[168:171], v[176:179], v[112:115]
	v_mfma_f32_16x16x32_bf16 v[100:103], v[144:147], v[192:195], v[100:103]
	v_mfma_f32_16x16x32_bf16 v[96:99], v[168:171], v[192:195], v[96:99]
	v_mfma_f32_16x16x32_bf16 v[84:87], v[144:147], v[204:207], v[84:87]
	v_mfma_f32_16x16x32_bf16 v[80:83], v[168:171], v[204:207], v[80:83]
	v_mfma_f32_16x16x32_bf16 v[68:71], v[144:147], v[212:215], v[68:71]
	v_mfma_f32_16x16x32_bf16 v[64:67], v[168:171], v[212:215], v[64:67]
	v_mfma_f32_16x16x32_bf16 v[116:119], v[148:151], v[180:183], v[116:119]
	v_mfma_f32_16x16x32_bf16 v[112:115], v[172:175], v[180:183], v[112:115]
	v_mfma_f32_16x16x32_bf16 v[100:103], v[148:151], v[198:201], v[100:103]
	v_mfma_f32_16x16x32_bf16 v[96:99], v[172:175], v[198:201], v[96:99]
	v_mfma_f32_16x16x32_bf16 v[84:87], v[148:151], v[208:211], v[84:87]
	v_mfma_f32_16x16x32_bf16 v[80:83], v[172:175], v[208:211], v[80:83]
	v_mfma_f32_16x16x32_bf16 v[68:71], v[148:151], v[216:219], v[68:71]
	v_mfma_f32_16x16x32_bf16 v[64:67], v[172:175], v[216:219], v[64:67]
	s_setprio 0
	s_barrier
	s_add_i32 s42, s59, s45
	v_lshl_add_u64 v[184:185], v[184:185], 0, s[26:27]
	s_mov_b32 m0, s42
	ds_read_b128 v[176:179], v191 offset:49152
	ds_read_b128 v[180:183], v191 offset:50176
	ds_read_b128 v[192:195], v191 offset:51200
	ds_read_b128 v[198:201], v191 offset:52224
	ds_read_b128 v[204:207], v191 offset:53248
	ds_read_b128 v[208:211], v191 offset:54272
	ds_read_b128 v[212:215], v191 offset:55296
	ds_read_b128 v[216:219], v191 offset:56320
	global_load_lds_dwordx4 v[184:185], off
	s_add_i32 m0, s42, 0x2000
	s_add_u32 s4, s4, 0x40080
	v_lshl_add_u64 v[184:185], v[220:221], 0, s[26:27]
	s_addc_u32 s5, s5, 0
	s_add_i32 s42, s60, s45
	global_load_lds_dwordx4 v[184:185], off
	v_lshl_add_u64 v[184:185], s[4:5], 0, v[154:155]
	s_mov_b32 m0, s42
	s_nop 0
	global_load_lds_dwordx4 v[184:185], off
	v_lshl_add_u64 v[184:185], s[4:5], 0, v[158:159]
	s_add_i32 m0, s42, 0x2000
	s_nop 0
	global_load_lds_dwordx4 v[184:185], off
	v_lshl_add_u64 v[184:185], v[222:223], 0, s[26:27]
	s_mov_b32 m0, s50
	s_nop 0
	global_load_lds_dwordx4 v[184:185], off
	v_lshl_add_u64 v[184:185], v[224:225], 0, s[26:27]
	s_mov_b32 m0, s51
	s_nop 0
	global_load_lds_dwordx4 v[184:185], off
	s_waitcnt vmcnt(8)
	s_waitcnt lgkmcnt(0)
	s_barrier
	s_setprio 1
	s_waitcnt lgkmcnt(0)
	v_mfma_f32_16x16x32_bf16 v[60:63], v[128:131], v[176:179], v[60:63]
	v_mfma_f32_16x16x32_bf16 v[56:59], v[136:139], v[176:179], v[56:59]
	v_mfma_f32_16x16x32_bf16 v[44:47], v[128:131], v[192:195], v[44:47]
	v_mfma_f32_16x16x32_bf16 v[40:43], v[136:139], v[192:195], v[40:43]
	v_mfma_f32_16x16x32_bf16 v[28:31], v[128:131], v[204:207], v[28:31]
	v_mfma_f32_16x16x32_bf16 v[24:27], v[136:139], v[204:207], v[24:27]
	v_mfma_f32_16x16x32_bf16 v[12:15], v[128:131], v[212:215], v[12:15]
	v_mfma_f32_16x16x32_bf16 v[8:11], v[136:139], v[212:215], v[8:11]
	v_mfma_f32_16x16x32_bf16 v[60:63], v[132:135], v[180:183], v[60:63]
	v_mfma_f32_16x16x32_bf16 v[56:59], v[140:143], v[180:183], v[56:59]
	v_mfma_f32_16x16x32_bf16 v[44:47], v[132:135], v[198:201], v[44:47]
	v_mfma_f32_16x16x32_bf16 v[40:43], v[140:143], v[198:201], v[40:43]
	v_mfma_f32_16x16x32_bf16 v[28:31], v[132:135], v[208:211], v[28:31]
	v_mfma_f32_16x16x32_bf16 v[24:27], v[140:143], v[208:211], v[24:27]
	v_mfma_f32_16x16x32_bf16 v[12:15], v[132:135], v[216:219], v[12:15]
	v_mfma_f32_16x16x32_bf16 v[8:11], v[140:143], v[216:219], v[8:11]
	s_setprio 0
	s_setprio 1
	v_mfma_f32_16x16x32_bf16 v[52:55], v[144:147], v[176:179], v[52:55]
	v_mfma_f32_16x16x32_bf16 v[48:51], v[168:171], v[176:179], v[48:51]
	v_mfma_f32_16x16x32_bf16 v[36:39], v[144:147], v[192:195], v[36:39]
	v_mfma_f32_16x16x32_bf16 v[32:35], v[168:171], v[192:195], v[32:35]
	v_mfma_f32_16x16x32_bf16 v[20:23], v[144:147], v[204:207], v[20:23]
	v_mfma_f32_16x16x32_bf16 v[16:19], v[168:171], v[204:207], v[16:19]
	v_mfma_f32_16x16x32_bf16 v[4:7], v[144:147], v[212:215], v[4:7]
	v_mfma_f32_16x16x32_bf16 v[0:3], v[168:171], v[212:215], v[0:3]
	v_mfma_f32_16x16x32_bf16 v[52:55], v[148:151], v[180:183], v[52:55]
	v_mfma_f32_16x16x32_bf16 v[48:51], v[172:175], v[180:183], v[48:51]
	v_mfma_f32_16x16x32_bf16 v[36:39], v[148:151], v[198:201], v[36:39]
	v_mfma_f32_16x16x32_bf16 v[32:35], v[172:175], v[198:201], v[32:35]
	v_mfma_f32_16x16x32_bf16 v[20:23], v[148:151], v[208:211], v[20:23]
	v_mfma_f32_16x16x32_bf16 v[16:19], v[172:175], v[208:211], v[16:19]
	v_mfma_f32_16x16x32_bf16 v[4:7], v[148:151], v[216:219], v[4:7]
	v_mfma_f32_16x16x32_bf16 v[0:3], v[172:175], v[216:219], v[0:3]
	s_setprio 0
	s_add_i32 s58, s58, 2
	s_add_u32 s22, s22, 0x100
	s_addc_u32 s23, s23, 0
	s_add_u32 s56, s56, 0x100
	s_addc_u32 s57, s57, 0
	s_cmp_gt_u32 s58, 13
	s_cbranch_scc1 .Lkexit_5
	s_barrier
	s_branch .LBB0_966

.LBB0_1048:
	ds_read_b128 v[146:149], v169
	ds_read_b128 v[150:153], v169 offset:1024
	ds_read_b128 v[154:157], v169 offset:2048
	ds_read_b128 v[160:163], v169 offset:3072
	ds_read_b128 v[178:181], v171
	ds_read_b128 v[182:185], v171 offset:1024
	ds_read_b128 v[186:189], v171 offset:2048
	ds_read_b128 v[190:193], v171 offset:3072
	s_add_u32 s4, s10, 0xfffc0080
	s_addc_u32 s5, s11, -1
	s_cmp_eq_u32 s55, 12
	s_cselect_b32 s13, s9, s5
	s_cselect_b32 s12, s31, s4
	s_cselect_b32 s5, s29, s54
	s_cselect_b32 s4, s52, s53
	v_lshl_add_u64 v[194:195], s[10:11], 0, v[138:139]
	s_add_i32 m0, s41, 0xc000
	ds_read_b128 v[198:201], v173
	ds_read_b128 v[204:207], v173 offset:1024
	ds_read_b128 v[208:211], v173 offset:2048
	ds_read_b128 v[212:215], v173 offset:3072
	ds_read_b128 v[216:219], v173 offset:4096
	ds_read_b128 v[220:223], v173 offset:5120
	ds_read_b128 v[224:227], v173 offset:6144
	ds_read_b128 v[228:231], v173 offset:7168
	global_load_lds_dwordx4 v[194:195], off
	v_lshl_add_u64 v[194:195], s[10:11], 0, v[140:141]
	s_add_i32 m0, s41, 0xe000
	s_nop 0
	global_load_lds_dwordx4 v[194:195], off
	s_waitcnt vmcnt(8)
	s_waitcnt lgkmcnt(0)
	s_barrier
	s_setprio 1
	s_waitcnt lgkmcnt(0)
	v_mfma_f32_16x16x32_bf16 v[124:127], v[146:149], v[198:201], v[124:127]
	v_mfma_f32_16x16x32_bf16 v[116:119], v[154:157], v[198:201], v[116:119]
	v_mfma_f32_16x16x32_bf16 v[108:111], v[146:149], v[208:211], v[108:111]
	v_mfma_f32_16x16x32_bf16 v[100:103], v[154:157], v[208:211], v[100:103]
	v_mfma_f32_16x16x32_bf16 v[92:95], v[146:149], v[216:219], v[92:95]
	v_mfma_f32_16x16x32_bf16 v[84:87], v[154:157], v[216:219], v[84:87]
	v_mfma_f32_16x16x32_bf16 v[76:79], v[146:149], v[224:227], v[76:79]
	v_mfma_f32_16x16x32_bf16 v[68:71], v[154:157], v[224:227], v[68:71]
	v_mfma_f32_16x16x32_bf16 v[124:127], v[150:153], v[204:207], v[124:127]
	v_mfma_f32_16x16x32_bf16 v[116:119], v[160:163], v[204:207], v[116:119]
	v_mfma_f32_16x16x32_bf16 v[108:111], v[150:153], v[212:215], v[108:111]
	v_mfma_f32_16x16x32_bf16 v[100:103], v[160:163], v[212:215], v[100:103]
	v_mfma_f32_16x16x32_bf16 v[92:95], v[150:153], v[220:223], v[92:95]
	v_mfma_f32_16x16x32_bf16 v[84:87], v[160:163], v[220:223], v[84:87]
	v_mfma_f32_16x16x32_bf16 v[76:79], v[150:153], v[228:231], v[76:79]
	v_mfma_f32_16x16x32_bf16 v[68:71], v[160:163], v[228:231], v[68:71]
	s_setprio 0
	s_setprio 1
	v_mfma_f32_16x16x32_bf16 v[120:123], v[178:181], v[198:201], v[120:123]
	v_mfma_f32_16x16x32_bf16 v[112:115], v[186:189], v[198:201], v[112:115]
	v_mfma_f32_16x16x32_bf16 v[104:107], v[178:181], v[208:211], v[104:107]
	v_mfma_f32_16x16x32_bf16 v[96:99], v[186:189], v[208:211], v[96:99]
	v_mfma_f32_16x16x32_bf16 v[88:91], v[178:181], v[216:219], v[88:91]
	v_mfma_f32_16x16x32_bf16 v[80:83], v[186:189], v[216:219], v[80:83]
	v_mfma_f32_16x16x32_bf16 v[72:75], v[178:181], v[224:227], v[72:75]
	v_mfma_f32_16x16x32_bf16 v[64:67], v[186:189], v[224:227], v[64:67]
	v_mfma_f32_16x16x32_bf16 v[120:123], v[182:185], v[204:207], v[120:123]
	v_mfma_f32_16x16x32_bf16 v[112:115], v[190:193], v[204:207], v[112:115]
	v_mfma_f32_16x16x32_bf16 v[104:107], v[182:185], v[212:215], v[104:107]
	v_mfma_f32_16x16x32_bf16 v[96:99], v[190:193], v[212:215], v[96:99]
	v_mfma_f32_16x16x32_bf16 v[88:91], v[182:185], v[220:223], v[88:91]
	v_mfma_f32_16x16x32_bf16 v[80:83], v[190:193], v[220:223], v[80:83]
	v_mfma_f32_16x16x32_bf16 v[72:75], v[182:185], v[228:231], v[72:75]
	v_mfma_f32_16x16x32_bf16 v[64:67], v[190:193], v[228:231], v[64:67]
	s_setprio 0
	s_barrier
	s_add_i32 s56, s48, s39
	v_lshl_add_u64 v[194:195], s[4:5], 0, v[132:133]
	s_mov_b32 m0, s56
	ds_read_b128 v[198:201], v173 offset:16384
	ds_read_b128 v[204:207], v173 offset:17408
	ds_read_b128 v[208:211], v173 offset:18432
	ds_read_b128 v[212:215], v173 offset:19456
	ds_read_b128 v[216:219], v173 offset:20480
	ds_read_b128 v[220:223], v173 offset:21504
	ds_read_b128 v[224:227], v173 offset:22528
	ds_read_b128 v[228:231], v173 offset:23552
	global_load_lds_dwordx4 v[194:195], off
	s_add_i32 m0, s56, 0x2000
	s_add_u32 s56, s4, 0x40000
	v_lshl_add_u64 v[232:233], s[4:5], 0, v[128:129]
	s_addc_u32 s57, s5, 0
	s_add_i32 s58, s49, s39
	global_load_lds_dwordx4 v[232:233], off
	v_lshl_add_u64 v[234:235], s[56:57], 0, v[132:133]
	s_mov_b32 m0, s58
	v_lshl_add_u64 v[236:237], s[12:13], 0, v[130:131]
	global_load_lds_dwordx4 v[234:235], off
	v_lshl_add_u64 v[234:235], s[56:57], 0, v[128:129]
	s_add_i32 m0, s58, 0x2000
	s_nop 0
	global_load_lds_dwordx4 v[234:235], off
	v_lshl_add_u64 v[234:235], s[12:13], 0, v[134:135]
	s_mov_b32 m0, s41
	s_nop 0
	global_load_lds_dwordx4 v[234:235], off
	s_mov_b32 m0, s42
	s_nop 0
	global_load_lds_dwordx4 v[236:237], off
	s_waitcnt vmcnt(8)
	s_waitcnt lgkmcnt(0)
	s_barrier
	s_setprio 1
	s_waitcnt lgkmcnt(0)
	v_mfma_f32_16x16x32_bf16 v[60:63], v[146:149], v[198:201], v[60:63]
	v_mfma_f32_16x16x32_bf16 v[52:55], v[154:157], v[198:201], v[52:55]
	v_mfma_f32_16x16x32_bf16 v[44:47], v[146:149], v[208:211], v[44:47]
	v_mfma_f32_16x16x32_bf16 v[36:39], v[154:157], v[208:211], v[36:39]
	v_mfma_f32_16x16x32_bf16 v[28:31], v[146:149], v[216:219], v[28:31]
	v_mfma_f32_16x16x32_bf16 v[20:23], v[154:157], v[216:219], v[20:23]
	v_mfma_f32_16x16x32_bf16 v[12:15], v[146:149], v[224:227], v[12:15]
	v_mfma_f32_16x16x32_bf16 v[4:7], v[154:157], v[224:227], v[4:7]
	v_mfma_f32_16x16x32_bf16 v[60:63], v[150:153], v[204:207], v[60:63]
	v_mfma_f32_16x16x32_bf16 v[52:55], v[160:163], v[204:207], v[52:55]
	v_mfma_f32_16x16x32_bf16 v[44:47], v[150:153], v[212:215], v[44:47]
	v_mfma_f32_16x16x32_bf16 v[36:39], v[160:163], v[212:215], v[36:39]
	v_mfma_f32_16x16x32_bf16 v[28:31], v[150:153], v[220:223], v[28:31]
	v_mfma_f32_16x16x32_bf16 v[20:23], v[160:163], v[220:223], v[20:23]
	v_mfma_f32_16x16x32_bf16 v[12:15], v[150:153], v[228:231], v[12:15]
	v_mfma_f32_16x16x32_bf16 v[4:7], v[160:163], v[228:231], v[4:7]
	s_setprio 0
	s_setprio 1
	v_mfma_f32_16x16x32_bf16 v[56:59], v[178:181], v[198:201], v[56:59]
	v_mfma_f32_16x16x32_bf16 v[48:51], v[186:189], v[198:201], v[48:51]
	v_mfma_f32_16x16x32_bf16 v[40:43], v[178:181], v[208:211], v[40:43]
	v_mfma_f32_16x16x32_bf16 v[32:35], v[186:189], v[208:211], v[32:35]
	v_mfma_f32_16x16x32_bf16 v[24:27], v[178:181], v[216:219], v[24:27]
	v_mfma_f32_16x16x32_bf16 v[16:19], v[186:189], v[216:219], v[16:19]
	v_mfma_f32_16x16x32_bf16 v[8:11], v[178:181], v[224:227], v[8:11]
	v_mfma_f32_16x16x32_bf16 v[0:3], v[186:189], v[224:227], v[0:3]
	v_mfma_f32_16x16x32_bf16 v[56:59], v[182:185], v[204:207], v[56:59]
	v_mfma_f32_16x16x32_bf16 v[48:51], v[190:193], v[204:207], v[48:51]
	v_mfma_f32_16x16x32_bf16 v[40:43], v[182:185], v[212:215], v[40:43]
	v_mfma_f32_16x16x32_bf16 v[32:35], v[190:193], v[212:215], v[32:35]
	v_mfma_f32_16x16x32_bf16 v[24:27], v[182:185], v[220:223], v[24:27]
	v_mfma_f32_16x16x32_bf16 v[16:19], v[190:193], v[220:223], v[16:19]
	v_mfma_f32_16x16x32_bf16 v[8:11], v[182:185], v[228:231], v[8:11]
	v_mfma_f32_16x16x32_bf16 v[0:3], v[190:193], v[228:231], v[0:3]
	s_setprio 0
	s_barrier
	s_add_i32 s56, 0, 0x18000
	v_add_u32_e32 v158, s56, v165
	s_add_i32 s57, 0, 0x1c000
	ds_read_b128 v[146:149], v158
	ds_read_b128 v[150:153], v158 offset:1024
	ds_read_b128 v[154:157], v158 offset:2048
	ds_read_b128 v[160:163], v158 offset:3072
	v_add_u32_e32 v158, s57, v165
	ds_read_b128 v[178:181], v158
	ds_read_b128 v[182:185], v158 offset:1024
	ds_read_b128 v[186:189], v158 offset:2048
	ds_read_b128 v[190:193], v158 offset:3072
	s_add_u32 s12, s12, 0x40000
	s_addc_u32 s13, s13, 0
	s_mov_b32 m0, s43
	v_lshl_add_u64 v[238:239], s[12:13], 0, v[134:135]
	ds_read_b128 v[198:201], v173 offset:32768
	ds_read_b128 v[204:207], v173 offset:33792
	ds_read_b128 v[208:211], v173 offset:34816
	ds_read_b128 v[212:215], v173 offset:35840
	ds_read_b128 v[216:219], v173 offset:36864
	ds_read_b128 v[220:223], v173 offset:37888
	ds_read_b128 v[224:227], v173 offset:38912
	ds_read_b128 v[228:231], v173 offset:39936
	global_load_lds_dwordx4 v[238:239], off
	v_lshl_add_u64 v[238:239], s[12:13], 0, v[130:131]
	s_mov_b32 m0, s44
	s_nop 0
	global_load_lds_dwordx4 v[238:239], off
	s_waitcnt vmcnt(8)
	s_waitcnt lgkmcnt(0)
	s_barrier
	s_setprio 1
	s_waitcnt lgkmcnt(0)
	v_mfma_f32_16x16x32_bf16 v[124:127], v[146:149], v[198:201], v[124:127]
	v_mfma_f32_16x16x32_bf16 v[116:119], v[154:157], v[198:201], v[116:119]
	v_mfma_f32_16x16x32_bf16 v[108:111], v[146:149], v[208:211], v[108:111]
	v_mfma_f32_16x16x32_bf16 v[100:103], v[154:157], v[208:211], v[100:103]
	v_mfma_f32_16x16x32_bf16 v[92:95], v[146:149], v[216:219], v[92:95]
	v_mfma_f32_16x16x32_bf16 v[84:87], v[154:157], v[216:219], v[84:87]
	v_mfma_f32_16x16x32_bf16 v[76:79], v[146:149], v[224:227], v[76:79]
	v_mfma_f32_16x16x32_bf16 v[68:71], v[154:157], v[224:227], v[68:71]
	v_mfma_f32_16x16x32_bf16 v[124:127], v[150:153], v[204:207], v[124:127]
	v_mfma_f32_16x16x32_bf16 v[116:119], v[160:163], v[204:207], v[116:119]
	v_mfma_f32_16x16x32_bf16 v[108:111], v[150:153], v[212:215], v[108:111]
	v_mfma_f32_16x16x32_bf16 v[100:103], v[160:163], v[212:215], v[100:103]
	v_mfma_f32_16x16x32_bf16 v[92:95], v[150:153], v[220:223], v[92:95]
	v_mfma_f32_16x16x32_bf16 v[84:87], v[160:163], v[220:223], v[84:87]
	v_mfma_f32_16x16x32_bf16 v[76:79], v[150:153], v[228:231], v[76:79]
	v_mfma_f32_16x16x32_bf16 v[68:71], v[160:163], v[228:231], v[68:71]
	s_setprio 0
	s_setprio 1
	v_mfma_f32_16x16x32_bf16 v[120:123], v[178:181], v[198:201], v[120:123]
	v_mfma_f32_16x16x32_bf16 v[112:115], v[186:189], v[198:201], v[112:115]
	v_mfma_f32_16x16x32_bf16 v[104:107], v[178:181], v[208:211], v[104:107]
	v_mfma_f32_16x16x32_bf16 v[96:99], v[186:189], v[208:211], v[96:99]
	v_mfma_f32_16x16x32_bf16 v[88:91], v[178:181], v[216:219], v[88:91]
	v_mfma_f32_16x16x32_bf16 v[80:83], v[186:189], v[216:219], v[80:83]
	v_mfma_f32_16x16x32_bf16 v[72:75], v[178:181], v[224:227], v[72:75]
	v_mfma_f32_16x16x32_bf16 v[64:67], v[186:189], v[224:227], v[64:67]
	v_mfma_f32_16x16x32_bf16 v[120:123], v[182:185], v[204:207], v[120:123]
	v_mfma_f32_16x16x32_bf16 v[112:115], v[190:193], v[204:207], v[112:115]
	v_mfma_f32_16x16x32_bf16 v[104:107], v[182:185], v[212:215], v[104:107]
	v_mfma_f32_16x16x32_bf16 v[96:99], v[190:193], v[212:215], v[96:99]
	v_mfma_f32_16x16x32_bf16 v[88:91], v[182:185], v[220:223], v[88:91]
	v_mfma_f32_16x16x32_bf16 v[80:83], v[190:193], v[220:223], v[80:83]
	v_mfma_f32_16x16x32_bf16 v[72:75], v[182:185], v[228:231], v[72:75]
	v_mfma_f32_16x16x32_bf16 v[64:67], v[190:193], v[228:231], v[64:67]
	s_setprio 0
	s_barrier
	s_add_i32 s12, s56, s39
	v_lshl_add_u64 v[194:195], v[194:195], 0, s[24:25]
	s_mov_b32 m0, s12
	ds_read_b128 v[198:201], v173 offset:49152
	ds_read_b128 v[204:207], v173 offset:50176
	ds_read_b128 v[208:211], v173 offset:51200
	ds_read_b128 v[212:215], v173 offset:52224
	ds_read_b128 v[216:219], v173 offset:53248
	ds_read_b128 v[220:223], v173 offset:54272
	ds_read_b128 v[224:227], v173 offset:55296
	ds_read_b128 v[228:231], v173 offset:56320
	global_load_lds_dwordx4 v[194:195], off
	s_add_i32 m0, s12, 0x2000
	s_add_u32 s4, s4, 0x40080
	v_lshl_add_u64 v[194:195], v[232:233], 0, s[24:25]
	s_addc_u32 s5, s5, 0
	s_add_i32 s12, s57, s39
	global_load_lds_dwordx4 v[194:195], off
	v_lshl_add_u64 v[194:195], s[4:5], 0, v[132:133]
	s_mov_b32 m0, s12
	s_nop 0
	global_load_lds_dwordx4 v[194:195], off
	v_lshl_add_u64 v[194:195], s[4:5], 0, v[128:129]
	s_add_i32 m0, s12, 0x2000
	s_nop 0
	global_load_lds_dwordx4 v[194:195], off
	v_lshl_add_u64 v[194:195], v[234:235], 0, s[24:25]
	s_mov_b32 m0, s46
	s_nop 0
	global_load_lds_dwordx4 v[194:195], off
	v_lshl_add_u64 v[194:195], v[236:237], 0, s[24:25]
	s_mov_b32 m0, s47
	s_nop 0
	global_load_lds_dwordx4 v[194:195], off
	s_waitcnt vmcnt(8)
	s_waitcnt lgkmcnt(0)
	s_barrier
	s_setprio 1
	s_waitcnt lgkmcnt(0)
	v_mfma_f32_16x16x32_bf16 v[60:63], v[146:149], v[198:201], v[60:63]
	v_mfma_f32_16x16x32_bf16 v[52:55], v[154:157], v[198:201], v[52:55]
	v_mfma_f32_16x16x32_bf16 v[44:47], v[146:149], v[208:211], v[44:47]
	v_mfma_f32_16x16x32_bf16 v[36:39], v[154:157], v[208:211], v[36:39]
	v_mfma_f32_16x16x32_bf16 v[28:31], v[146:149], v[216:219], v[28:31]
	v_mfma_f32_16x16x32_bf16 v[20:23], v[154:157], v[216:219], v[20:23]
	v_mfma_f32_16x16x32_bf16 v[12:15], v[146:149], v[224:227], v[12:15]
	v_mfma_f32_16x16x32_bf16 v[4:7], v[154:157], v[224:227], v[4:7]
	v_mfma_f32_16x16x32_bf16 v[60:63], v[150:153], v[204:207], v[60:63]
	v_mfma_f32_16x16x32_bf16 v[52:55], v[160:163], v[204:207], v[52:55]
	v_mfma_f32_16x16x32_bf16 v[44:47], v[150:153], v[212:215], v[44:47]
	v_mfma_f32_16x16x32_bf16 v[36:39], v[160:163], v[212:215], v[36:39]
	v_mfma_f32_16x16x32_bf16 v[28:31], v[150:153], v[220:223], v[28:31]
	v_mfma_f32_16x16x32_bf16 v[20:23], v[160:163], v[220:223], v[20:23]
	v_mfma_f32_16x16x32_bf16 v[12:15], v[150:153], v[228:231], v[12:15]
	v_mfma_f32_16x16x32_bf16 v[4:7], v[160:163], v[228:231], v[4:7]
	s_setprio 0
	s_setprio 1
	v_mfma_f32_16x16x32_bf16 v[56:59], v[178:181], v[198:201], v[56:59]
	v_mfma_f32_16x16x32_bf16 v[48:51], v[186:189], v[198:201], v[48:51]
	v_mfma_f32_16x16x32_bf16 v[40:43], v[178:181], v[208:211], v[40:43]
	v_mfma_f32_16x16x32_bf16 v[32:35], v[186:189], v[208:211], v[32:35]
	v_mfma_f32_16x16x32_bf16 v[24:27], v[178:181], v[216:219], v[24:27]
	v_mfma_f32_16x16x32_bf16 v[16:19], v[186:189], v[216:219], v[16:19]
	v_mfma_f32_16x16x32_bf16 v[8:11], v[178:181], v[224:227], v[8:11]
	v_mfma_f32_16x16x32_bf16 v[0:3], v[186:189], v[224:227], v[0:3]
	v_mfma_f32_16x16x32_bf16 v[56:59], v[182:185], v[204:207], v[56:59]
	v_mfma_f32_16x16x32_bf16 v[48:51], v[190:193], v[204:207], v[48:51]
	v_mfma_f32_16x16x32_bf16 v[40:43], v[182:185], v[212:215], v[40:43]
	v_mfma_f32_16x16x32_bf16 v[32:35], v[190:193], v[212:215], v[32:35]
	v_mfma_f32_16x16x32_bf16 v[24:27], v[182:185], v[220:223], v[24:27]
	v_mfma_f32_16x16x32_bf16 v[16:19], v[190:193], v[220:223], v[16:19]
	v_mfma_f32_16x16x32_bf16 v[8:11], v[182:185], v[228:231], v[8:11]
	v_mfma_f32_16x16x32_bf16 v[0:3], v[190:193], v[228:231], v[0:3]
	s_setprio 0
	s_add_i32 s55, s55, 2
	s_add_u32 s10, s10, 0x100
	s_addc_u32 s11, s11, 0
	s_add_u32 s53, s53, 0x100
	s_addc_u32 s54, s54, 0
	s_cmp_gt_u32 s55, 13
	s_cbranch_scc1 .Lkexit_6
	s_barrier
	s_branch .LBB0_1048
.Lkexit_6:
	s_and_b64 vcc, exec, s[26:27]
	s_cbranch_vccz .LBB0_1051
	s_barrier

.LBB0_1124:
	ds_read_b128 v[128:131], v189
	ds_read_b128 v[132:135], v189 offset:1024
	ds_read_b128 v[136:139], v189 offset:2048
	ds_read_b128 v[140:143], v189 offset:3072
	ds_read_b128 v[144:147], v190
	ds_read_b128 v[148:151], v190 offset:1024
	ds_read_b128 v[168:171], v190 offset:2048
	ds_read_b128 v[172:175], v190 offset:3072
	s_add_u32 s34, s30, 0x100
	s_addc_u32 s35, s31, 0
	s_cmp_eq_u32 s56, 40
	s_cselect_b32 s39, s9, s35
	s_cselect_b32 s38, s8, s34
	s_cselect_b32 s37, s29, s55
	s_cselect_b32 s36, s28, s54
	v_lshl_add_u64 v[184:185], s[30:31], 0, v[160:161]
	s_add_i32 m0, s42, 0xc000
	ds_read_b128 v[176:179], v191
	ds_read_b128 v[180:183], v191 offset:1024
	ds_read_b128 v[192:195], v191 offset:2048
	ds_read_b128 v[198:201], v191 offset:3072
	ds_read_b128 v[204:207], v191 offset:4096
	ds_read_b128 v[208:211], v191 offset:5120
	ds_read_b128 v[212:215], v191 offset:6144
	ds_read_b128 v[216:219], v191 offset:7168
	global_load_lds_dwordx4 v[184:185], off
	v_lshl_add_u64 v[184:185], s[30:31], 0, v[162:163]
	s_add_i32 m0, s42, 0xe000
	s_nop 0
	global_load_lds_dwordx4 v[184:185], off
	s_waitcnt vmcnt(8)
	s_waitcnt lgkmcnt(0)
	s_barrier
	s_setprio 1
	s_waitcnt lgkmcnt(0)
	v_mfma_f32_16x16x32_bf16 v[124:127], v[128:131], v[176:179], v[124:127]
	v_mfma_f32_16x16x32_bf16 v[120:123], v[136:139], v[176:179], v[120:123]
	v_mfma_f32_16x16x32_bf16 v[108:111], v[128:131], v[192:195], v[108:111]
	v_mfma_f32_16x16x32_bf16 v[104:107], v[136:139], v[192:195], v[104:107]
	v_mfma_f32_16x16x32_bf16 v[92:95], v[128:131], v[204:207], v[92:95]
	v_mfma_f32_16x16x32_bf16 v[88:91], v[136:139], v[204:207], v[88:91]
	v_mfma_f32_16x16x32_bf16 v[76:79], v[128:131], v[212:215], v[76:79]
	v_mfma_f32_16x16x32_bf16 v[72:75], v[136:139], v[212:215], v[72:75]
	v_mfma_f32_16x16x32_bf16 v[124:127], v[132:135], v[180:183], v[124:127]
	v_mfma_f32_16x16x32_bf16 v[120:123], v[140:143], v[180:183], v[120:123]
	v_mfma_f32_16x16x32_bf16 v[108:111], v[132:135], v[198:201], v[108:111]
	v_mfma_f32_16x16x32_bf16 v[104:107], v[140:143], v[198:201], v[104:107]
	v_mfma_f32_16x16x32_bf16 v[92:95], v[132:135], v[208:211], v[92:95]
	v_mfma_f32_16x16x32_bf16 v[88:91], v[140:143], v[208:211], v[88:91]
	v_mfma_f32_16x16x32_bf16 v[76:79], v[132:135], v[216:219], v[76:79]
	v_mfma_f32_16x16x32_bf16 v[72:75], v[140:143], v[216:219], v[72:75]
	s_setprio 0
	s_setprio 1
	v_mfma_f32_16x16x32_bf16 v[116:119], v[144:147], v[176:179], v[116:119]
	v_mfma_f32_16x16x32_bf16 v[112:115], v[168:171], v[176:179], v[112:115]
	v_mfma_f32_16x16x32_bf16 v[100:103], v[144:147], v[192:195], v[100:103]
	v_mfma_f32_16x16x32_bf16 v[96:99], v[168:171], v[192:195], v[96:99]
	v_mfma_f32_16x16x32_bf16 v[84:87], v[144:147], v[204:207], v[84:87]
	v_mfma_f32_16x16x32_bf16 v[80:83], v[168:171], v[204:207], v[80:83]
	v_mfma_f32_16x16x32_bf16 v[68:71], v[144:147], v[212:215], v[68:71]
	v_mfma_f32_16x16x32_bf16 v[64:67], v[168:171], v[212:215], v[64:67]
	v_mfma_f32_16x16x32_bf16 v[116:119], v[148:151], v[180:183], v[116:119]
	v_mfma_f32_16x16x32_bf16 v[112:115], v[172:175], v[180:183], v[112:115]
	v_mfma_f32_16x16x32_bf16 v[100:103], v[148:151], v[198:201], v[100:103]
	v_mfma_f32_16x16x32_bf16 v[96:99], v[172:175], v[198:201], v[96:99]
	v_mfma_f32_16x16x32_bf16 v[84:87], v[148:151], v[208:211], v[84:87]
	v_mfma_f32_16x16x32_bf16 v[80:83], v[172:175], v[208:211], v[80:83]
	v_mfma_f32_16x16x32_bf16 v[68:71], v[148:151], v[216:219], v[68:71]
	v_mfma_f32_16x16x32_bf16 v[64:67], v[172:175], v[216:219], v[64:67]
	s_setprio 0
	s_barrier
	s_add_i32 s30, s48, s41
	v_lshl_add_u64 v[184:185], s[36:37], 0, v[154:155]
	s_mov_b32 m0, s30
	ds_read_b128 v[176:179], v191 offset:16384
	ds_read_b128 v[180:183], v191 offset:17408
	ds_read_b128 v[192:195], v191 offset:18432
	ds_read_b128 v[198:201], v191 offset:19456
	ds_read_b128 v[204:207], v191 offset:20480
	ds_read_b128 v[208:211], v191 offset:21504
	ds_read_b128 v[212:215], v191 offset:22528
	ds_read_b128 v[216:219], v191 offset:23552
	global_load_lds_dwordx4 v[184:185], off
	s_add_i32 m0, s30, 0x2000
	s_add_u32 s30, s36, 0xb0000
	v_lshl_add_u64 v[220:221], s[36:37], 0, v[158:159]
	s_addc_u32 s31, s37, 0
	s_add_i32 s57, s49, s41
	global_load_lds_dwordx4 v[220:221], off
	v_lshl_add_u64 v[222:223], s[30:31], 0, v[154:155]
	s_mov_b32 m0, s57
	v_lshl_add_u64 v[224:225], s[38:39], 0, v[156:157]
	global_load_lds_dwordx4 v[222:223], off
	v_lshl_add_u64 v[222:223], s[30:31], 0, v[158:159]
	s_add_i32 m0, s57, 0x2000
	s_nop 0
	global_load_lds_dwordx4 v[222:223], off
	v_lshl_add_u64 v[222:223], s[38:39], 0, v[152:153]
	s_mov_b32 m0, s42
	s_nop 0
	global_load_lds_dwordx4 v[222:223], off
	s_mov_b32 m0, s33
	s_nop 0
	global_load_lds_dwordx4 v[224:225], off
	s_waitcnt vmcnt(8)
	s_waitcnt lgkmcnt(0)
	s_barrier
	s_setprio 1
	s_waitcnt lgkmcnt(0)
	v_mfma_f32_16x16x32_bf16 v[60:63], v[128:131], v[176:179], v[60:63]
	v_mfma_f32_16x16x32_bf16 v[56:59], v[136:139], v[176:179], v[56:59]
	v_mfma_f32_16x16x32_bf16 v[44:47], v[128:131], v[192:195], v[44:47]
	v_mfma_f32_16x16x32_bf16 v[40:43], v[136:139], v[192:195], v[40:43]
	v_mfma_f32_16x16x32_bf16 v[28:31], v[128:131], v[204:207], v[28:31]
	v_mfma_f32_16x16x32_bf16 v[24:27], v[136:139], v[204:207], v[24:27]
	v_mfma_f32_16x16x32_bf16 v[12:15], v[128:131], v[212:215], v[12:15]
	v_mfma_f32_16x16x32_bf16 v[8:11], v[136:139], v[212:215], v[8:11]
	v_mfma_f32_16x16x32_bf16 v[60:63], v[132:135], v[180:183], v[60:63]
	v_mfma_f32_16x16x32_bf16 v[56:59], v[140:143], v[180:183], v[56:59]
	v_mfma_f32_16x16x32_bf16 v[44:47], v[132:135], v[198:201], v[44:47]
	v_mfma_f32_16x16x32_bf16 v[40:43], v[140:143], v[198:201], v[40:43]
	v_mfma_f32_16x16x32_bf16 v[28:31], v[132:135], v[208:211], v[28:31]
	v_mfma_f32_16x16x32_bf16 v[24:27], v[140:143], v[208:211], v[24:27]
	v_mfma_f32_16x16x32_bf16 v[12:15], v[132:135], v[216:219], v[12:15]
	v_mfma_f32_16x16x32_bf16 v[8:11], v[140:143], v[216:219], v[8:11]
	s_setprio 0
	s_setprio 1
	v_mfma_f32_16x16x32_bf16 v[52:55], v[144:147], v[176:179], v[52:55]
	v_mfma_f32_16x16x32_bf16 v[48:51], v[168:171], v[176:179], v[48:51]
	v_mfma_f32_16x16x32_bf16 v[36:39], v[144:147], v[192:195], v[36:39]
	v_mfma_f32_16x16x32_bf16 v[32:35], v[168:171], v[192:195], v[32:35]
	v_mfma_f32_16x16x32_bf16 v[20:23], v[144:147], v[204:207], v[20:23]
	v_mfma_f32_16x16x32_bf16 v[16:19], v[168:171], v[204:207], v[16:19]
	v_mfma_f32_16x16x32_bf16 v[4:7], v[144:147], v[212:215], v[4:7]
	v_mfma_f32_16x16x32_bf16 v[0:3], v[168:171], v[212:215], v[0:3]
	v_mfma_f32_16x16x32_bf16 v[52:55], v[148:151], v[180:183], v[52:55]
	v_mfma_f32_16x16x32_bf16 v[48:51], v[172:175], v[180:183], v[48:51]
	v_mfma_f32_16x16x32_bf16 v[36:39], v[148:151], v[198:201], v[36:39]
	v_mfma_f32_16x16x32_bf16 v[32:35], v[172:175], v[198:201], v[32:35]
	v_mfma_f32_16x16x32_bf16 v[20:23], v[148:151], v[208:211], v[20:23]
	v_mfma_f32_16x16x32_bf16 v[16:19], v[172:175], v[208:211], v[16:19]
	v_mfma_f32_16x16x32_bf16 v[4:7], v[148:151], v[216:219], v[4:7]
	v_mfma_f32_16x16x32_bf16 v[0:3], v[172:175], v[216:219], v[0:3]
	s_setprio 0
	s_barrier
	s_add_i32 s57, 0, 0x18000
	s_add_i32 s58, 0, 0x1c000
	v_add_u32_e32 v140, s57, v187
	v_add_u32_e32 v172, s58, v187
	ds_read_b128 v[128:131], v140
	ds_read_b128 v[132:135], v140 offset:1024
	ds_read_b128 v[136:139], v140 offset:2048
	ds_read_b128 v[140:143], v140 offset:3072
	ds_read_b128 v[144:147], v172
	ds_read_b128 v[148:151], v172 offset:1024
	ds_read_b128 v[168:171], v172 offset:2048
	ds_read_b128 v[172:175], v172 offset:3072
	s_add_u32 s30, s38, 0xb0000
	s_addc_u32 s31, s39, 0
	s_mov_b32 m0, s43
	v_lshl_add_u64 v[226:227], s[30:31], 0, v[152:153]
	ds_read_b128 v[176:179], v191 offset:32768
	ds_read_b128 v[180:183], v191 offset:33792
	ds_read_b128 v[192:195], v191 offset:34816
	ds_read_b128 v[198:201], v191 offset:35840
	ds_read_b128 v[204:207], v191 offset:36864
	ds_read_b128 v[208:211], v191 offset:37888
	ds_read_b128 v[212:215], v191 offset:38912
	ds_read_b128 v[216:219], v191 offset:39936
	global_load_lds_dwordx4 v[226:227], off
	v_lshl_add_u64 v[226:227], s[30:31], 0, v[156:157]
	s_mov_b32 m0, s44
	s_nop 0
	global_load_lds_dwordx4 v[226:227], off
	s_waitcnt vmcnt(8)
	s_waitcnt lgkmcnt(0)
	s_barrier
	s_setprio 1
	s_waitcnt lgkmcnt(0)
	v_mfma_f32_16x16x32_bf16 v[124:127], v[128:131], v[176:179], v[124:127]
	v_mfma_f32_16x16x32_bf16 v[120:123], v[136:139], v[176:179], v[120:123]
	v_mfma_f32_16x16x32_bf16 v[108:111], v[128:131], v[192:195], v[108:111]
	v_mfma_f32_16x16x32_bf16 v[104:107], v[136:139], v[192:195], v[104:107]
	v_mfma_f32_16x16x32_bf16 v[92:95], v[128:131], v[204:207], v[92:95]
	v_mfma_f32_16x16x32_bf16 v[88:91], v[136:139], v[204:207], v[88:91]
	v_mfma_f32_16x16x32_bf16 v[76:79], v[128:131], v[212:215], v[76:79]
	v_mfma_f32_16x16x32_bf16 v[72:75], v[136:139], v[212:215], v[72:75]
	v_mfma_f32_16x16x32_bf16 v[124:127], v[132:135], v[180:183], v[124:127]
	v_mfma_f32_16x16x32_bf16 v[120:123], v[140:143], v[180:183], v[120:123]
	v_mfma_f32_16x16x32_bf16 v[108:111], v[132:135], v[198:201], v[108:111]
	v_mfma_f32_16x16x32_bf16 v[104:107], v[140:143], v[198:201], v[104:107]
	v_mfma_f32_16x16x32_bf16 v[92:95], v[132:135], v[208:211], v[92:95]
	v_mfma_f32_16x16x32_bf16 v[88:91], v[140:143], v[208:211], v[88:91]
	v_mfma_f32_16x16x32_bf16 v[76:79], v[132:135], v[216:219], v[76:79]
	v_mfma_f32_16x16x32_bf16 v[72:75], v[140:143], v[216:219], v[72:75]
	s_setprio 0
	s_setprio 1
	v_mfma_f32_16x16x32_bf16 v[116:119], v[144:147], v[176:179], v[116:119]
	v_mfma_f32_16x16x32_bf16 v[112:115], v[168:171], v[176:179], v[112:115]
	v_mfma_f32_16x16x32_bf16 v[100:103], v[144:147], v[192:195], v[100:103]
	v_mfma_f32_16x16x32_bf16 v[96:99], v[168:171], v[192:195], v[96:99]
	v_mfma_f32_16x16x32_bf16 v[84:87], v[144:147], v[204:207], v[84:87]
	v_mfma_f32_16x16x32_bf16 v[80:83], v[168:171], v[204:207], v[80:83]
	v_mfma_f32_16x16x32_bf16 v[68:71], v[144:147], v[212:215], v[68:71]
	v_mfma_f32_16x16x32_bf16 v[64:67], v[168:171], v[212:215], v[64:67]
	v_mfma_f32_16x16x32_bf16 v[116:119], v[148:151], v[180:183], v[116:119]
	v_mfma_f32_16x16x32_bf16 v[112:115], v[172:175], v[180:183], v[112:115]
	v_mfma_f32_16x16x32_bf16 v[100:103], v[148:151], v[198:201], v[100:103]
	v_mfma_f32_16x16x32_bf16 v[96:99], v[172:175], v[198:201], v[96:99]
	v_mfma_f32_16x16x32_bf16 v[84:87], v[148:151], v[208:211], v[84:87]
	v_mfma_f32_16x16x32_bf16 v[80:83], v[172:175], v[208:211], v[80:83]
	v_mfma_f32_16x16x32_bf16 v[68:71], v[148:151], v[216:219], v[68:71]
	v_mfma_f32_16x16x32_bf16 v[64:67], v[172:175], v[216:219], v[64:67]
	s_setprio 0
	s_barrier
	s_add_i32 s30, s57, s41
	v_lshl_add_u64 v[184:185], v[184:185], 0, s[24:25]
	s_mov_b32 m0, s30
	ds_read_b128 v[176:179], v191 offset:49152
	ds_read_b128 v[180:183], v191 offset:50176
	ds_read_b128 v[192:195], v191 offset:51200
	ds_read_b128 v[198:201], v191 offset:52224
	ds_read_b128 v[204:207], v191 offset:53248
	ds_read_b128 v[208:211], v191 offset:54272
	ds_read_b128 v[212:215], v191 offset:55296
	ds_read_b128 v[216:219], v191 offset:56320
	global_load_lds_dwordx4 v[184:185], off
	s_add_i32 m0, s30, 0x2000
	s_add_u32 s30, s36, 0xb0080
	v_lshl_add_u64 v[184:185], v[220:221], 0, s[24:25]
	s_addc_u32 s31, s37, 0
	s_add_i32 s36, s58, s41
	global_load_lds_dwordx4 v[184:185], off
	v_lshl_add_u64 v[184:185], s[30:31], 0, v[154:155]
	s_mov_b32 m0, s36
	s_nop 0
	global_load_lds_dwordx4 v[184:185], off
	v_lshl_add_u64 v[184:185], s[30:31], 0, v[158:159]
	s_add_i32 m0, s36, 0x2000
	s_nop 0
	global_load_lds_dwordx4 v[184:185], off
	v_lshl_add_u64 v[184:185], v[222:223], 0, s[24:25]
	s_mov_b32 m0, s46
	s_nop 0
	global_load_lds_dwordx4 v[184:185], off
	v_lshl_add_u64 v[184:185], v[224:225], 0, s[24:25]
	s_mov_b32 m0, s47
	s_nop 0
	global_load_lds_dwordx4 v[184:185], off
	s_waitcnt vmcnt(8)
	s_waitcnt lgkmcnt(0)
	s_barrier
	s_setprio 1
	s_waitcnt lgkmcnt(0)
	v_mfma_f32_16x16x32_bf16 v[60:63], v[128:131], v[176:179], v[60:63]
	v_mfma_f32_16x16x32_bf16 v[56:59], v[136:139], v[176:179], v[56:59]
	v_mfma_f32_16x16x32_bf16 v[44:47], v[128:131], v[192:195], v[44:47]
	v_mfma_f32_16x16x32_bf16 v[40:43], v[136:139], v[192:195], v[40:43]
	v_mfma_f32_16x16x32_bf16 v[28:31], v[128:131], v[204:207], v[28:31]
	v_mfma_f32_16x16x32_bf16 v[24:27], v[136:139], v[204:207], v[24:27]
	v_mfma_f32_16x16x32_bf16 v[12:15], v[128:131], v[212:215], v[12:15]
	v_mfma_f32_16x16x32_bf16 v[8:11], v[136:139], v[212:215], v[8:11]
	v_mfma_f32_16x16x32_bf16 v[60:63], v[132:135], v[180:183], v[60:63]
	v_mfma_f32_16x16x32_bf16 v[56:59], v[140:143], v[180:183], v[56:59]
	v_mfma_f32_16x16x32_bf16 v[44:47], v[132:135], v[198:201], v[44:47]
	v_mfma_f32_16x16x32_bf16 v[40:43], v[140:143], v[198:201], v[40:43]
	v_mfma_f32_16x16x32_bf16 v[28:31], v[132:135], v[208:211], v[28:31]
	v_mfma_f32_16x16x32_bf16 v[24:27], v[140:143], v[208:211], v[24:27]
	v_mfma_f32_16x16x32_bf16 v[12:15], v[132:135], v[216:219], v[12:15]
	v_mfma_f32_16x16x32_bf16 v[8:11], v[140:143], v[216:219], v[8:11]
	s_setprio 0
	s_setprio 1
	v_mfma_f32_16x16x32_bf16 v[52:55], v[144:147], v[176:179], v[52:55]
	v_mfma_f32_16x16x32_bf16 v[48:51], v[168:171], v[176:179], v[48:51]
	v_mfma_f32_16x16x32_bf16 v[36:39], v[144:147], v[192:195], v[36:39]
	v_mfma_f32_16x16x32_bf16 v[32:35], v[168:171], v[192:195], v[32:35]
	v_mfma_f32_16x16x32_bf16 v[20:23], v[144:147], v[204:207], v[20:23]
	v_mfma_f32_16x16x32_bf16 v[16:19], v[168:171], v[204:207], v[16:19]
	v_mfma_f32_16x16x32_bf16 v[4:7], v[144:147], v[212:215], v[4:7]
	v_mfma_f32_16x16x32_bf16 v[0:3], v[168:171], v[212:215], v[0:3]
	v_mfma_f32_16x16x32_bf16 v[52:55], v[148:151], v[180:183], v[52:55]
	v_mfma_f32_16x16x32_bf16 v[48:51], v[172:175], v[180:183], v[48:51]
	v_mfma_f32_16x16x32_bf16 v[36:39], v[148:151], v[198:201], v[36:39]
	v_mfma_f32_16x16x32_bf16 v[32:35], v[172:175], v[198:201], v[32:35]
	v_mfma_f32_16x16x32_bf16 v[20:23], v[148:151], v[208:211], v[20:23]
	v_mfma_f32_16x16x32_bf16 v[16:19], v[172:175], v[208:211], v[16:19]
	v_mfma_f32_16x16x32_bf16 v[4:7], v[148:151], v[216:219], v[4:7]
	v_mfma_f32_16x16x32_bf16 v[0:3], v[172:175], v[216:219], v[0:3]
	s_setprio 0
	s_add_i32 s56, s56, 2
	s_add_u32 s54, s54, 0x100
	s_addc_u32 s55, s55, 0
	s_cmp_gt_u32 s56, 41
	s_mov_b64 s[30:31], s[34:35]
	s_cbranch_scc1 .Lkexit_7
	s_barrier
	s_branch .LBB0_1124
